# rg_prompt: conv taps j=0..2 of token blocks 1..3 rebuilt from the j=3 loads with DPP row shifts (9 fewer row-gather loads per channel block)
# speedup vs baseline: 1.0087x; 1.0087x over previous
.LBB0_209:
	s_andn2_saveexec_b64 s[54:55], s[80:81]
	v_fma_f32 v82, v81, s92, 0.5
	v_fma_f32 v82, -v81, v82, 1.0
	v_mul_f32_e32 v170, v81, v82
	s_or_b64 exec, exec, s[54:55]
	v_lshl_add_u64 v[138:139], s[74:75], 0, v[118:119]
	v_add_co_u32_e32 v84, vcc, 0x13094000, v138
	v_max_f32_e64 v76, -v76, -v76
	s_nop 0
	v_addc_co_u32_e32 v85, vcc, 0, v139, vcc
	global_load_dwordx2 v[168:169], v[84:85], off offset:2560
	v_add_co_u32_e32 v84, vcc, 0x13098000, v138
	v_max_f32_e32 v76, 0, v76
	s_nop 0
	v_addc_co_u32_e32 v85, vcc, 0, v139, vcc
	global_load_dwordx2 v[164:165], v[84:85], off offset:3072
	v_add_co_u32_e32 v84, vcc, 0x1309c000, v138
	v_add_f32_e32 v185, v76, v80
	s_nop 0
	v_addc_co_u32_e32 v85, vcc, 0, v139, vcc
	v_add_co_u32_e32 v140, vcc, 0x130a1000, v138
	global_load_dwordx2 v[162:163], v[84:85], off offset:3584
	s_nop 0
	v_addc_co_u32_e32 v141, vcc, 0, v139, vcc
	global_load_dwordx2 v[166:167], v[140:141], off
	global_load_dwordx2 v[142:143], v[140:141], off offset:2048
	v_add_co_u32_e32 v140, vcc, s97, v138
	v_mfma_f32_16x16x32_bf16 v[84:87], v[72:75], v[0:3], 0
	s_nop 0
	v_addc_co_u32_e32 v141, vcc, 0, v139, vcc
	global_load_dwordx2 v[140:141], v[140:141], off
	s_nop 0
	s_nop 0
	s_nop 0
	s_mov_b32 s100, 0x130e3000
	s_mov_b32 s101, 0
	v_lshl_add_u64 v[248:249], v[138:139], 0, s[100:101]
	global_load_dwordx2 v[216:217], v[248:249], off
	s_mov_b32 s100, 0x130e3800
	s_mov_b32 s101, 0
	v_lshl_add_u64 v[248:249], v[138:139], 0, s[100:101]
	global_load_dwordx2 v[218:219], v[248:249], off
	s_mov_b32 s100, 0x130e6000
	s_mov_b32 s101, 0
	v_lshl_add_u64 v[248:249], v[138:139], 0, s[100:101]
	global_load_dwordx2 v[220:221], v[248:249], off
	s_nop 0
	s_nop 0
	s_nop 0
	s_mov_b32 s100, 0x13125000
	s_mov_b32 s101, 0
	v_lshl_add_u64 v[248:249], v[138:139], 0, s[100:101]
	global_load_dwordx2 v[228:229], v[248:249], off
	s_mov_b32 s100, 0x13125800
	s_mov_b32 s101, 0
	v_lshl_add_u64 v[248:249], v[138:139], 0, s[100:101]
	global_load_dwordx2 v[230:231], v[248:249], off
	s_mov_b32 s100, 0x13128000
	s_mov_b32 s101, 0
	v_lshl_add_u64 v[248:249], v[138:139], 0, s[100:101]
	global_load_dwordx2 v[232:233], v[248:249], off
	s_nop 0
	s_nop 0
	s_nop 0
	s_mov_b32 s100, 0x13167000
	s_mov_b32 s101, 0
	v_lshl_add_u64 v[248:249], v[138:139], 0, s[100:101]
	global_load_dwordx2 v[242:243], v[248:249], off
	s_mov_b32 s100, 0x13167800
	s_mov_b32 s101, 0
	v_lshl_add_u64 v[248:249], v[138:139], 0, s[100:101]
	global_load_dwordx2 v[244:245], v[248:249], off
	s_mov_b32 s100, 0x1316a000
	s_mov_b32 s101, 0
	v_lshl_add_u64 v[248:249], v[138:139], 0, s[100:101]
	global_load_dwordx2 v[246:247], v[248:249], off
	v_mfma_f32_16x16x32_bf16 v[84:87], v[60:63], v[16:19], v[84:87]
	v_mfma_f32_16x16x32_bf16 v[80:83], v[68:71], v[0:3], 0
	v_mfma_f32_16x16x32_bf16 v[80:83], v[64:67], v[16:19], v[80:83]
	s_nop 0
	s_nop 4
	s_nop 0
	s_waitcnt vmcnt(16)
	v_add_f32_e32 v76, v56, v84
	v_mul_f32_e32 v76, 0xbfb8aa3b, v76
	v_exp_f32_e32 v76, v76
	s_nop 0
	v_add_f32_e32 v76, 1.0, v76
	v_rcp_f32_e32 v76, v76
	s_nop 0
	v_mul_f32_e32 v76, 0xc1000000, v76
	v_mul_f32_e32 v76, v185, v76
	v_add_f32_e32 v171, v76, v76
	v_cmp_nlt_f32_e32 vcc, s93, v171
	s_and_saveexec_b64 s[54:55], vcc
	s_xor_b64 s[54:55], exec, s[54:55]
	v_mul_f32_e32 v84, 0x3fb8aa3b, v171
	v_exp_f32_e32 v84, v84
	s_nop 0
	v_sub_f32_e32 v84, 1.0, v84
	s_andn2_saveexec_b64 s[54:55], s[54:55]
	v_fma_f32 v84, v171, s94, 0.5
	v_fma_f32 v84, v171, v84, 1.0
	v_mul_f32_e64 v84, v84, -v171
	s_or_b64 exec, exec, s[54:55]
	v_add_f32_e32 v85, v57, v85
	v_mul_f32_e32 v85, 0xbfb8aa3b, v85
	v_exp_f32_e32 v85, v85
	v_max_f32_e64 v77, -v77, -v77
	v_max_f32_e32 v77, 0, v77
	v_add_f32_e32 v186, v77, v144
	v_add_f32_e32 v85, 1.0, v85
	v_rcp_f32_e32 v85, v85
	s_nop 0
	v_mul_f32_e32 v77, 0xc1000000, v85
	v_mul_f32_e32 v77, v186, v77
	v_add_f32_e32 v144, v77, v77
	v_cmp_nlt_f32_e32 vcc, s93, v144
	s_and_saveexec_b64 s[54:55], vcc
	s_xor_b64 s[54:55], exec, s[54:55]
	v_mul_f32_e32 v85, 0x3fb8aa3b, v144
	v_exp_f32_e32 v85, v85
	s_nop 0
	v_sub_f32_e32 v85, 1.0, v85
	s_andn2_saveexec_b64 s[54:55], s[54:55]
	v_fma_f32 v85, v144, s94, 0.5
	v_fma_f32 v85, v144, v85, 1.0
	v_mul_f32_e64 v85, v85, -v144
	s_or_b64 exec, exec, s[54:55]
	v_add_f32_e32 v86, v58, v86
	v_mul_f32_e32 v86, 0xbfb8aa3b, v86
	v_exp_f32_e32 v86, v86
	v_max_f32_e64 v78, -v78, -v78
	v_max_f32_e32 v78, 0, v78
	v_add_f32_e32 v187, v78, v147
	v_add_f32_e32 v86, 1.0, v86
	v_rcp_f32_e32 v86, v86
	s_nop 0
	v_mul_f32_e32 v78, 0xc1000000, v86
	v_mul_f32_e32 v78, v187, v78
	v_add_f32_e32 v144, v78, v78
	v_cmp_nlt_f32_e32 vcc, s93, v144
	s_and_saveexec_b64 s[54:55], vcc
	s_xor_b64 s[54:55], exec, s[54:55]
	v_mul_f32_e32 v86, 0x3fb8aa3b, v144
	v_exp_f32_e32 v86, v86
	s_nop 0
	v_sub_f32_e32 v86, 1.0, v86
	s_andn2_saveexec_b64 s[54:55], s[54:55]
	v_fma_f32 v86, v144, s94, 0.5
	v_fma_f32 v86, v144, v86, 1.0
	v_mul_f32_e64 v86, v86, -v144
	s_or_b64 exec, exec, s[54:55]
	v_add_f32_e32 v87, v59, v87
	v_mul_f32_e32 v87, 0xbfb8aa3b, v87
	v_exp_f32_e32 v87, v87
	v_max_f32_e64 v79, -v79, -v79
	v_max_f32_e32 v79, 0, v79
	v_add_f32_e32 v188, v79, v170
	v_add_f32_e32 v87, 1.0, v87
	v_rcp_f32_e32 v87, v87
	s_nop 0
	v_mul_f32_e32 v79, 0xc1000000, v87
	v_mul_f32_e32 v87, v188, v79
	v_add_f32_e32 v144, v87, v87
	v_cmp_nlt_f32_e32 vcc, s93, v144
	s_and_saveexec_b64 s[54:55], vcc
	s_xor_b64 s[54:55], exec, s[54:55]
	v_mul_f32_e32 v79, 0x3fb8aa3b, v144
	v_exp_f32_e32 v79, v79
	s_nop 0
	v_sub_f32_e32 v79, 1.0, v79
	s_andn2_saveexec_b64 s[54:55], s[54:55]
	v_fma_f32 v79, v144, s94, 0.5
	v_fma_f32 v79, v144, v79, 1.0
	v_mul_f32_e64 v79, v79, -v144
	s_or_b64 exec, exec, s[54:55]
	s_nop 0
	s_nop 0
	s_waitcnt vmcnt(15)
	v_add_f32_e32 v82, v34, v82
	v_mul_f32_e32 v82, 0xbfb8aa3b, v82
	v_exp_f32_e32 v82, v82
	v_add_f32_e32 v81, v33, v81
	s_nop 0
	s_nop 0
	s_waitcnt vmcnt(14)
	v_cndmask_b32_e64 v144, v169, 0, s[28:29]
	v_cndmask_b32_e64 v147, v168, 0, s[28:29]
	v_add_f32_e32 v82, 1.0, v82
	v_add_f32_e32 v83, v35, v83
	v_mul_f32_e32 v81, 0xbfb8aa3b, v81
	v_lshlrev_b32_e32 v152, 16, v147
	v_and_b32_e32 v153, 0xffff0000, v147
	v_lshlrev_b32_e32 v168, 16, v144
	v_and_b32_e32 v169, 0xffff0000, v144
	s_nop 0
	s_nop 0
	s_waitcnt vmcnt(13)
	v_cndmask_b32_e64 v144, v165, 0, s[30:31]
	v_cndmask_b32_e64 v147, v164, 0, s[30:31]
	v_rcp_f32_e32 v82, v82
	v_sqrt_f32_e32 v86, v86
	v_mul_f32_e32 v83, 0xbfb8aa3b, v83
	v_exp_f32_e32 v81, v81
	v_pk_fma_f32 v[168:169], v[50:51], v[168:169], v[54:55]
	v_pk_fma_f32 v[152:153], v[48:49], v[152:153], v[52:53]
	v_lshlrev_b32_e32 v164, 16, v147
	v_and_b32_e32 v165, 0xffff0000, v147
	v_lshlrev_b32_e32 v170, 16, v144
	v_and_b32_e32 v171, 0xffff0000, v144
	s_nop 0
	s_nop 0
	s_waitcnt vmcnt(12)
	v_cndmask_b32_e64 v144, v163, 0, s[34:35]
	v_cndmask_b32_e64 v147, v162, 0, s[34:35]
	v_exp_f32_e32 v83, v83
	v_pk_fma_f32 v[152:153], v[44:45], v[164:165], v[152:153]
	v_pk_fma_f32 v[164:165], v[46:47], v[170:171], v[168:169]
	v_lshlrev_b32_e32 v162, 16, v147
	v_and_b32_e32 v163, 0xffff0000, v147
	v_lshlrev_b32_e32 v168, 16, v144
	v_and_b32_e32 v169, 0xffff0000, v144
	s_nop 0
	s_nop 0
	s_waitcnt vmcnt(11)
	v_mov_b32_dpp v194, v166 row_shl:13 row_mask:0xf bank_mask:0xf
	v_mov_b32_dpp v195, v167 row_shl:13 row_mask:0xf bank_mask:0xf
	v_mov_b32_dpp v212, v166 row_shl:14 row_mask:0xf bank_mask:0xf
	v_mov_b32_dpp v213, v167 row_shl:14 row_mask:0xf bank_mask:0xf
	v_mov_b32_dpp v214, v166 row_shl:15 row_mask:0xf bank_mask:0xf
	v_mov_b32_dpp v215, v167 row_shl:15 row_mask:0xf bank_mask:0xf
	v_cndmask_b32_e64 v144, v167, 0, s[64:65]
	v_cndmask_b32_e64 v147, v166, 0, s[64:65]
	v_add_f32_e32 v80, v32, v80
	v_pk_fma_f32 v[164:165], v[42:43], v[168:169], v[164:165]
	v_pk_fma_f32 v[152:153], v[40:41], v[162:163], v[152:153]
	v_lshlrev_b32_e32 v162, 16, v147
	v_and_b32_e32 v163, 0xffff0000, v147
	v_lshlrev_b32_e32 v166, 16, v144
	v_and_b32_e32 v167, 0xffff0000, v144
	v_mul_f32_e32 v80, 0xbfb8aa3b, v80
	v_pk_fma_f32 v[152:153], v[36:37], v[162:163], v[152:153]
	v_pk_fma_f32 v[162:163], v[38:39], v[166:167], v[164:165]
	v_mul_f32_e32 v82, v82, v86
	v_add_f32_e32 v81, 1.0, v81
	v_exp_f32_e32 v80, v80
	v_mul_f32_e32 v162, v162, v82
	v_add_f32_e32 v82, 1.0, v83
	v_rcp_f32_e32 v81, v81
	v_sqrt_f32_e32 v83, v85
	v_add_f32_e32 v80, 1.0, v80
	v_rcp_f32_e32 v80, v80
	v_mul_f32_e32 v76, 0x3fb8aa3b, v76
	v_mul_f32_e32 v81, v81, v83
	v_sqrt_f32_e32 v83, v84
	v_exp_f32_e32 v76, v76
	v_mul_f32_e32 v77, 0x3fb8aa3b, v77
	v_mul_f32_e32 v85, 0x3fb8aa3b, v87
	v_mul_f32_e32 v80, v80, v83
	v_mul_f32_e32 v87, v152, v80
	v_exp_f32_e32 v77, v77
	v_mov_b32_e32 v80, 0
	v_rcp_f32_e32 v82, v82
	v_mul_f32_e32 v78, 0x3fb8aa3b, v78
	v_sqrt_f32_e32 v79, v79
	v_mov_b32_dpp v80, v87 row_shr:1 row_mask:0xf bank_mask:0xf
	v_mul_f32_e32 v153, v153, v81
	v_exp_f32_e32 v78, v78
	v_fmac_f32_e32 v87, v76, v80
	v_mov_b32_e32 v80, 0
	v_exp_f32_e32 v85, v85
	v_mul_f32_e32 v79, v82, v79
	v_mov_b32_dpp v80, v153 row_shr:1 row_mask:0xf bank_mask:0xf
	v_fmac_f32_e32 v153, v77, v80
	v_mov_b32_e32 v80, 0
	v_mul_f32_e32 v152, v163, v79
	v_mov_b32_e32 v79, 1.0
	v_mov_b32_dpp v80, v162 row_shr:1 row_mask:0xf bank_mask:0xf
	v_fmac_f32_e32 v162, v78, v80
	v_mov_b32_e32 v80, 0
	v_mov_b32_dpp v79, v76 row_shr:1 row_mask:0xf bank_mask:0xf
	v_mul_f32_e32 v76, v76, v79
	v_mov_b32_dpp v80, v152 row_shr:1 row_mask:0xf bank_mask:0xf
	v_mov_b32_e32 v79, 1.0
	v_fmac_f32_e32 v152, v85, v80
	v_mov_b32_e32 v80, 1.0
	v_mov_b32_e32 v81, 0
	v_mov_b32_dpp v79, v77 row_shr:1 row_mask:0xf bank_mask:0xf
	v_mov_b32_dpp v80, v76 row_shr:2 row_mask:0xf bank_mask:0xf
	v_mov_b32_dpp v81, v87 row_shr:2 row_mask:0xf bank_mask:0xf
	v_mul_f32_e32 v77, v77, v79
	v_mov_b32_e32 v79, 1.0
	v_fmac_f32_e32 v87, v76, v81
	v_mul_f32_e32 v147, v76, v80
	v_mov_b32_e32 v76, 1.0
	v_mov_b32_dpp v79, v78 row_shr:1 row_mask:0xf bank_mask:0xf
	v_mul_f32_e32 v78, v78, v79
	v_mov_b32_dpp v76, v77 row_shr:2 row_mask:0xf bank_mask:0xf
	v_mov_b32_e32 v79, 1.0
	v_mul_f32_e32 v163, v77, v76
	v_mov_b32_e32 v76, 1.0
	v_mov_b32_dpp v79, v85 row_shr:1 row_mask:0xf bank_mask:0xf
	v_mul_f32_e32 v79, v85, v79
	v_mov_b32_dpp v76, v78 row_shr:2 row_mask:0xf bank_mask:0xf
	v_mul_f32_e32 v164, v78, v76
	v_mov_b32_e32 v76, 1.0
	v_mov_b32_e32 v80, 0
	s_nop 0
	s_nop 0
	s_waitcnt vmcnt(9)
	v_lshlrev_b32_e32 v84, 16, v140
	v_mov_b32_dpp v76, v79 row_shr:2 row_mask:0xf bank_mask:0xf
	v_mul_f32_e32 v165, v79, v76
	v_mov_b32_e32 v76, 0
	v_mov_b32_dpp v80, v153 row_shr:2 row_mask:0xf bank_mask:0xf
	v_fmac_f32_e32 v153, v77, v80
	v_mov_b32_dpp v76, v87 row_shr:4 row_mask:0xf bank_mask:0xf
	v_mov_b32_e32 v77, 0
	v_fmac_f32_e32 v87, v147, v76
	v_mov_b32_e32 v76, 0
	v_mov_b32_dpp v77, v162 row_shr:2 row_mask:0xf bank_mask:0xf
	v_fmac_f32_e32 v162, v78, v77
	v_mov_b32_dpp v76, v153 row_shr:4 row_mask:0xf bank_mask:0xf
	v_mov_b32_e32 v77, 0
	v_fmac_f32_e32 v153, v163, v76
	v_mov_b32_e32 v76, 0
	v_mov_b32_dpp v77, v152 row_shr:2 row_mask:0xf bank_mask:0xf
	v_fmac_f32_e32 v152, v79, v77
	v_mov_b32_dpp v76, v162 row_shr:4 row_mask:0xf bank_mask:0xf
	v_fmac_f32_e32 v162, v164, v76
	v_mov_b32_e32 v76, 0
	v_mov_b32_e32 v77, 1.0
	v_mul_f32_e32 v84, 0xbfb8aa3b, v84
	v_mov_b32_dpp v76, v152 row_shr:4 row_mask:0xf bank_mask:0xf
	v_mov_b32_dpp v77, v147 row_shr:4 row_mask:0xf bank_mask:0xf
	v_fmac_f32_e32 v152, v165, v76
	v_lshlrev_b32_e32 v76, 16, v142
	v_and_b32_e32 v78, 0xffff0000, v142
	v_and_b32_e32 v142, 0xffff0000, v140
	v_exp_f32_e32 v140, v84
	v_pk_mul_f32 v[84:85], v[146:147], v[76:77]
	v_mul_f32_e32 v77, 0x3d372713, v76
	v_mul_f32_e32 v77, v77, v76
	v_fmac_f32_e32 v76, v77, v76
	v_mul_f32_e32 v76, 0x3f4c422a, v76
	v_add_f32_e32 v76, v76, v76
	v_mul_f32_e32 v76, 0x3fb8aa3b, v76
	v_exp_f32_e32 v76, v76
	v_add_f32_e32 v77, 1.0, v140
	v_rcp_f32_e32 v144, v77
	v_mov_b32_e32 v77, 1.0
	v_add_f32_e32 v76, 1.0, v76
	v_rcp_f32_e32 v76, v76
	v_mov_b32_e32 v86, 0
	v_mov_b32_dpp v77, v85 row_shr:8 row_mask:0xf bank_mask:0xf
	v_mov_b32_e32 v79, 1.0
	v_fma_f32 v76, v76, -2.0, 1.0
	v_add_f32_e32 v76, 1.0, v76
	v_mov_b32_dpp v86, v87 row_shr:8 row_mask:0xf bank_mask:0xf
	v_pk_mul_f32 v[76:77], v[84:85], v[76:77]
	v_lshlrev_b32_e32 v169, 16, v141
	v_and_b32_e32 v170, 0xffff0000, v141
	v_fmac_f32_e32 v87, v85, v86
	v_pk_mul_f32 v[140:141], v[144:145], v[76:77]
	v_mov_b32_dpp v79, v163 row_shr:4 row_mask:0xf bank_mask:0xf
	v_add_f32_e32 v76, v141, v87
	v_mov_b32_e32 v147, v163
	v_lshlrev_b32_e32 v80, 16, v143
	v_and_b32_e32 v82, 0xffff0000, v143
	v_mul_f32_e32 v171, v140, v76
	v_mul_f32_e32 v76, 0xbfb8aa3b, v142
	v_pk_mul_f32 v[142:143], v[146:147], v[78:79]
	v_mul_f32_e32 v79, 0x3d372713, v78
	v_mul_f32_e32 v79, v79, v78
	v_fmac_f32_e32 v78, v79, v78
	v_mul_f32_e32 v78, 0x3f4c422a, v78
	v_add_f32_e32 v78, v78, v78
	v_exp_f32_e32 v76, v76
	v_mul_f32_e32 v78, 0x3fb8aa3b, v78
	v_exp_f32_e32 v78, v78
	ds_bpermute_b32 v86, v184, v77
	v_add_f32_e32 v76, 1.0, v76
	v_rcp_f32_e32 v144, v76
	v_add_f32_e32 v76, 1.0, v78
	v_rcp_f32_e32 v76, v76
	v_mul_f32_e32 v163, v140, v77
	v_mov_b32_e32 v77, 1.0
	v_mov_b32_e32 v166, 0
	v_fma_f32 v76, v76, -2.0, 1.0
	v_mov_b32_dpp v77, v143 row_shr:8 row_mask:0xf bank_mask:0xf
	v_add_f32_e32 v76, 1.0, v76
	v_mov_b32_dpp v166, v153 row_shr:8 row_mask:0xf bank_mask:0xf
	v_pk_mul_f32 v[76:77], v[142:143], v[76:77]
	v_fmac_f32_e32 v153, v143, v166
	v_pk_mul_f32 v[78:79], v[144:145], v[76:77]
	v_mov_b32_e32 v81, 1.0
	v_add_f32_e32 v76, v79, v153
	v_mul_f32_e32 v79, 0x3d372713, v80
	v_mov_b32_dpp v81, v164 row_shr:4 row_mask:0xf bank_mask:0xf
	v_mov_b32_e32 v147, v164
	v_mul_f32_e32 v79, v79, v80
	v_pk_mul_f32 v[140:141], v[146:147], v[80:81]
	v_fmac_f32_e32 v80, v79, v80
	v_mul_f32_e32 v79, 0x3f4c422a, v80
	ds_bpermute_b32 v85, v184, v153
	v_mul_f32_e32 v153, v78, v76
	v_mul_f32_e32 v76, 0xbfb8aa3b, v169
	v_add_f32_e32 v79, v79, v79
	v_exp_f32_e32 v76, v76
	v_mul_f32_e32 v79, 0x3fb8aa3b, v79
	v_exp_f32_e32 v79, v79
	ds_bpermute_b32 v84, v184, v87
	v_add_f32_e32 v76, 1.0, v76
	v_rcp_f32_e32 v144, v76
	v_add_f32_e32 v76, 1.0, v79
	v_rcp_f32_e32 v76, v76
	ds_bpermute_b32 v87, v184, v77
	v_mul_f32_e32 v164, v78, v77
	v_mov_b32_e32 v77, 1.0
	v_fma_f32 v76, v76, -2.0, 1.0
	v_mov_b32_e32 v167, 0
	v_mov_b32_dpp v77, v141 row_shr:8 row_mask:0xf bank_mask:0xf
	v_add_f32_e32 v76, 1.0, v76
	v_mov_b32_dpp v167, v162 row_shr:8 row_mask:0xf bank_mask:0xf
	v_pk_mul_f32 v[76:77], v[140:141], v[76:77]
	v_fmac_f32_e32 v162, v141, v167
	v_pk_mul_f32 v[78:79], v[144:145], v[76:77]
	v_mov_b32_e32 v83, 1.0
	v_add_f32_e32 v76, v79, v162
	v_mul_f32_e32 v79, 0x3d372713, v82
	v_mov_b32_dpp v83, v165 row_shr:4 row_mask:0xf bank_mask:0xf
	v_mov_b32_e32 v147, v165
	v_mul_f32_e32 v79, v79, v82
	v_pk_mul_f32 v[80:81], v[146:147], v[82:83]
	v_fmac_f32_e32 v82, v79, v82
	v_mul_f32_e32 v79, 0x3f4c422a, v82
	ds_bpermute_b32 v142, v184, v162
	v_mul_f32_e32 v162, v78, v76
	v_mul_f32_e32 v76, 0xbfb8aa3b, v170
	v_add_f32_e32 v79, v79, v79
	v_exp_f32_e32 v76, v76
	v_mul_f32_e32 v79, 0x3fb8aa3b, v79
	v_exp_f32_e32 v79, v79
	ds_bpermute_b32 v140, v184, v77
	v_add_f32_e32 v76, 1.0, v76
	v_rcp_f32_e32 v144, v76
	v_add_f32_e32 v76, 1.0, v79
	v_rcp_f32_e32 v76, v76
	v_mul_f32_e32 v82, v78, v77
	v_mov_b32_e32 v77, 1.0
	v_mov_b32_e32 v168, 0
	v_fma_f32 v76, v76, -2.0, 1.0
	v_mov_b32_dpp v77, v81 row_shr:8 row_mask:0xf bank_mask:0xf
	v_add_f32_e32 v76, 1.0, v76
	v_mov_b32_dpp v168, v152 row_shr:8 row_mask:0xf bank_mask:0xf
	v_pk_mul_f32 v[76:77], v[80:81], v[76:77]
	v_fmac_f32_e32 v152, v81, v168
	v_pk_mul_f32 v[78:79], v[144:145], v[76:77]
	ds_bpermute_b32 v141, v184, v77
	v_add_f32_e32 v76, v79, v152
	v_mul_f32_e32 v79, v78, v76
	ds_bpermute_b32 v143, v184, v152
	v_mul_f32_e32 v83, v78, v77
	v_cvt_pk_bf16_f32 v77, v162, v79
	v_lshl_add_u64 v[78:79], s[74:75], 0, v[134:135]
	v_add_co_u32_e32 v80, vcc, s95, v78
	v_cvt_pk_bf16_f32 v76, v171, v153
	s_nop 1
	v_addc_co_u32_e32 v81, vcc, 0, v79, vcc
	v_add_co_u32_e32 v78, vcc, s96, v78
	global_store_dwordx2 v[80:81], v[76:77], off
	s_nop 0
	v_addc_co_u32_e32 v79, vcc, 0, v79, vcc
	v_cvt_pk_bf16_f32 v76, v163, v164
	v_cvt_pk_bf16_f32 v77, v82, v83
	global_store_dwordx2 v[78:79], v[76:77], off
	s_mov_b32 s54, 0x130d6000
	v_add_co_u32_e32 v80, vcc, s54, v138
	s_mov_b32 s54, 0x130da000
	s_nop 0
	v_addc_co_u32_e32 v81, vcc, 0, v139, vcc
	s_nop 0
	v_add_co_u32_e32 v80, vcc, s54, v138
	s_mov_b32 s54, 0x130de000
	s_nop 0
	v_addc_co_u32_e32 v81, vcc, 0, v139, vcc
	s_nop 0
	v_add_co_u32_e32 v80, vcc, s54, v138
	s_mov_b32 s54, 0x130e3000
	s_nop 0
	v_addc_co_u32_e32 v81, vcc, 0, v139, vcc
	v_add_co_u32_e32 v152, vcc, s54, v138
	s_nop 0
	s_nop 0
	v_addc_co_u32_e32 v153, vcc, 0, v139, vcc
	s_nop 0
	s_nop 0
	v_add_co_u32_e32 v152, vcc, 0x130e6000, v138
	v_mfma_f32_16x16x32_bf16 v[80:83], v[72:75], v[4:7], 0
	s_nop 0
	v_addc_co_u32_e32 v153, vcc, 0, v139, vcc
	s_nop 0
	v_mfma_f32_16x16x32_bf16 v[80:83], v[60:63], v[20:23], v[80:83]
	v_mfma_f32_16x16x32_bf16 v[76:79], v[68:71], v[4:7], 0
	v_mfma_f32_16x16x32_bf16 v[76:79], v[64:67], v[20:23], v[76:79]
	s_nop 5
	v_add_f32_e32 v80, v56, v80
	v_mul_f32_e32 v80, 0xbfb8aa3b, v80
	v_exp_f32_e32 v80, v80
	s_nop 0
	v_add_f32_e32 v80, 1.0, v80
	v_rcp_f32_e32 v80, v80
	s_nop 0
	v_mul_f32_e32 v80, 0xc1000000, v80
	v_mul_f32_e32 v80, v185, v80
	v_add_f32_e32 v147, v80, v80
	v_cmp_nlt_f32_e32 vcc, s93, v147
	s_and_saveexec_b64 s[54:55], vcc
	s_xor_b64 s[54:55], exec, s[54:55]
	v_mul_f32_e32 v144, 0x3fb8aa3b, v147
	v_exp_f32_e32 v144, v144
	s_nop 0
	v_sub_f32_e32 v144, 1.0, v144
	s_andn2_saveexec_b64 s[54:55], s[54:55]
	v_fma_f32 v144, v147, s94, 0.5
	v_fma_f32 v144, v147, v144, 1.0
	v_mul_f32_e64 v144, v144, -v147
	s_or_b64 exec, exec, s[54:55]
	v_add_f32_e32 v81, v57, v81
	v_mul_f32_e32 v81, 0xbfb8aa3b, v81
	v_exp_f32_e32 v81, v81
	s_nop 0
	v_add_f32_e32 v81, 1.0, v81
	v_rcp_f32_e32 v81, v81
	s_nop 0
	v_mul_f32_e32 v81, 0xc1000000, v81
	v_mul_f32_e32 v81, v186, v81
	v_add_f32_e32 v174, v81, v81
	v_cmp_nlt_f32_e32 vcc, s93, v174
	s_and_saveexec_b64 s[54:55], vcc
	s_xor_b64 s[54:55], exec, s[54:55]
	v_mul_f32_e32 v147, 0x3fb8aa3b, v174
	v_exp_f32_e32 v147, v147
	s_nop 0
	v_sub_f32_e32 v147, 1.0, v147
	s_andn2_saveexec_b64 s[54:55], s[54:55]
	v_fma_f32 v147, v174, s94, 0.5
	v_fma_f32 v147, v174, v147, 1.0
	v_mul_f32_e64 v147, v147, -v174
	s_or_b64 exec, exec, s[54:55]
	v_add_f32_e32 v82, v58, v82
	v_mul_f32_e32 v82, 0xbfb8aa3b, v82
	v_exp_f32_e32 v82, v82
	s_nop 0
	v_add_f32_e32 v82, 1.0, v82
	v_rcp_f32_e32 v82, v82
	s_nop 0
	v_mul_f32_e32 v82, 0xc1000000, v82
	v_mul_f32_e32 v82, v187, v82
	v_add_f32_e32 v175, v82, v82
	v_cmp_nlt_f32_e32 vcc, s93, v175
	s_and_saveexec_b64 s[54:55], vcc
	s_xor_b64 s[54:55], exec, s[54:55]
	v_mul_f32_e32 v152, 0x3fb8aa3b, v175
	v_exp_f32_e32 v152, v152
	s_nop 0
	v_sub_f32_e32 v174, 1.0, v152
	s_andn2_saveexec_b64 s[54:55], s[54:55]
	v_fma_f32 v152, v175, s94, 0.5
	v_fma_f32 v152, v175, v152, 1.0
	v_mul_f32_e64 v174, v152, -v175
	s_or_b64 exec, exec, s[54:55]
	v_add_f32_e32 v83, v59, v83
	v_mul_f32_e32 v83, 0xbfb8aa3b, v83
	v_exp_f32_e32 v83, v83
	s_nop 0
	v_add_f32_e32 v83, 1.0, v83
	v_rcp_f32_e32 v83, v83
	s_nop 0
	v_mul_f32_e32 v83, 0xc1000000, v83
	v_mul_f32_e32 v175, v188, v83
	v_add_f32_e32 v176, v175, v175
	v_cmp_nlt_f32_e32 vcc, s93, v176
	s_and_saveexec_b64 s[54:55], vcc
	s_xor_b64 s[54:55], exec, s[54:55]
	v_mul_f32_e32 v83, 0x3fb8aa3b, v176
	v_exp_f32_e32 v83, v83
	s_nop 0
	v_sub_f32_e32 v83, 1.0, v83
	s_andn2_saveexec_b64 s[54:55], s[54:55]
	v_fma_f32 v83, v176, s94, 0.5
	v_fma_f32 v83, v176, v83, 1.0
	v_mul_f32_e64 v83, v83, -v176
	s_or_b64 exec, exec, s[54:55]
	v_add_f32_e32 v78, v34, v78
	v_mul_f32_e32 v78, 0xbfb8aa3b, v78
	s_nop 0
	s_nop 0
	s_waitcnt vmcnt(10)
	v_mov_b32_dpp v194, v216 row_shr:3 row_mask:0xf bank_mask:0xf
	v_mov_b32_dpp v195, v217 row_shr:3 row_mask:0xf bank_mask:0xf
	v_mov_b32_dpp v212, v216 row_shr:2 row_mask:0xf bank_mask:0xf
	v_mov_b32_dpp v213, v217 row_shr:2 row_mask:0xf bank_mask:0xf
	v_mov_b32_dpp v214, v216 row_shr:1 row_mask:0xf bank_mask:0xf
	v_mov_b32_dpp v215, v217 row_shr:1 row_mask:0xf bank_mask:0xf
	v_cndmask_b32_e64 v171, v195, 0, s[36:37]
	v_cndmask_b32_e64 v153, v194, 0, s[36:37]
	v_exp_f32_e32 v78, v78
	v_lshlrev_b32_e32 v152, 16, v153
	v_and_b32_e32 v153, 0xffff0000, v153
	v_lshlrev_b32_e32 v170, 16, v171
	v_and_b32_e32 v171, 0xffff0000, v171
	s_nop 0
	s_nop 0
	v_cndmask_b32_e64 v177, v213, 0, s[38:39]
	v_cndmask_b32_e64 v163, v212, 0, s[38:39]
	v_pk_fma_f32 v[170:171], v[50:51], v[170:171], v[54:55]
	v_pk_fma_f32 v[152:153], v[48:49], v[152:153], v[52:53]
	v_lshlrev_b32_e32 v162, 16, v163
	v_and_b32_e32 v163, 0xffff0000, v163
	v_lshlrev_b32_e32 v176, 16, v177
	v_and_b32_e32 v177, 0xffff0000, v177
	v_pk_fma_f32 v[152:153], v[44:45], v[162:163], v[152:153]
	v_pk_fma_f32 v[162:163], v[46:47], v[176:177], v[170:171]
	s_nop 0
	s_nop 0
	v_cndmask_b32_e64 v171, v215, 0, s[40:41]
	v_cndmask_b32_e64 v169, v214, 0, s[40:41]
	v_add_f32_e32 v77, v33, v77
	v_lshlrev_b32_e32 v168, 16, v169
	v_and_b32_e32 v169, 0xffff0000, v169
	v_add_f32_e32 v78, 1.0, v78
	v_add_f32_e32 v79, v35, v79
	v_mul_f32_e32 v77, 0xbfb8aa3b, v77
	v_pk_fma_f32 v[152:153], v[40:41], v[168:169], v[152:153]
	s_nop 0
	s_nop 0
	v_mov_b32_dpp v222, v216 row_shl:13 row_mask:0xf bank_mask:0xf
	v_mov_b32_dpp v223, v217 row_shl:13 row_mask:0xf bank_mask:0xf
	v_mov_b32_dpp v224, v216 row_shl:14 row_mask:0xf bank_mask:0xf
	v_mov_b32_dpp v225, v217 row_shl:14 row_mask:0xf bank_mask:0xf
	v_mov_b32_dpp v226, v216 row_shl:15 row_mask:0xf bank_mask:0xf
	v_mov_b32_dpp v227, v217 row_shl:15 row_mask:0xf bank_mask:0xf
	v_cndmask_b32_e64 v169, v216, 0, s[64:65]
	v_rcp_f32_e32 v78, v78
	v_sqrt_f32_e32 v172, v174
	v_mul_f32_e32 v79, 0xbfb8aa3b, v79
	v_exp_f32_e32 v77, v77
	v_lshlrev_b32_e32 v170, 16, v171
	v_and_b32_e32 v171, 0xffff0000, v171
	v_exp_f32_e32 v79, v79
	v_pk_fma_f32 v[162:163], v[42:43], v[170:171], v[162:163]
	v_cndmask_b32_e64 v171, v217, 0, s[64:65]
	v_add_f32_e32 v76, v32, v76
	v_lshlrev_b32_e32 v168, 16, v169
	v_and_b32_e32 v169, 0xffff0000, v169
	v_lshlrev_b32_e32 v170, 16, v171
	v_and_b32_e32 v171, 0xffff0000, v171
	v_mul_f32_e32 v76, 0xbfb8aa3b, v76
	v_pk_fma_f32 v[152:153], v[36:37], v[168:169], v[152:153]
	v_pk_fma_f32 v[168:169], v[38:39], v[170:171], v[162:163]
	v_mul_f32_e32 v78, v78, v172
	v_add_f32_e32 v77, 1.0, v77
	v_exp_f32_e32 v76, v76
	v_mul_f32_e32 v171, v168, v78
	v_add_f32_e32 v78, 1.0, v79
	v_rcp_f32_e32 v77, v77
	v_sqrt_f32_e32 v79, v147
	v_add_f32_e32 v76, 1.0, v76
	v_rcp_f32_e32 v76, v76
	v_rcp_f32_e32 v78, v78
	v_mul_f32_e32 v77, v77, v79
	v_sqrt_f32_e32 v79, v144
	v_mul_f32_e32 v80, 0x3fb8aa3b, v80
	v_exp_f32_e32 v80, v80
	v_mul_f32_e32 v144, v153, v77
	v_mul_f32_e32 v76, v76, v79
	v_sqrt_f32_e32 v79, v83
	v_mul_f32_e32 v168, v152, v76
	v_mul_f32_e32 v76, 0x3fb8aa3b, v81
	v_exp_f32_e32 v76, v76
	v_mul_f32_e32 v78, v78, v79
	v_mul_f32_e32 v172, v169, v78
	v_mov_b32_e32 v78, 1.0
	v_mov_b32_e32 v79, v145
	v_mul_f32_e32 v77, 0x3fb8aa3b, v82
	v_mov_b32_dpp v78, v80 row_shr:1 row_mask:0xf bank_mask:0xf
	v_mov_b32_dpp v79, v168 row_shr:1 row_mask:0xf bank_mask:0xf
	v_exp_f32_e32 v77, v77
	v_fmac_f32_e32 v168, v80, v79
	v_mul_f32_e32 v78, v80, v78
	v_mov_b32_e32 v80, v145
	v_mul_f32_e32 v147, 0x3fb8aa3b, v175
	v_exp_f32_e32 v147, v147
	v_mov_b32_dpp v80, v144 row_shr:1 row_mask:0xf bank_mask:0xf
	v_mov_b32_e32 v79, 1.0
	v_fmac_f32_e32 v144, v76, v80
	v_mov_b32_e32 v80, v145
	v_mov_b32_dpp v79, v76 row_shr:1 row_mask:0xf bank_mask:0xf
	v_mul_f32_e32 v76, v76, v79
	v_mov_b32_dpp v80, v171 row_shr:1 row_mask:0xf bank_mask:0xf
	v_mov_b32_e32 v79, 1.0
	v_fmac_f32_e32 v171, v77, v80
	v_mov_b32_e32 v80, v145
	v_mov_b32_dpp v79, v77 row_shr:1 row_mask:0xf bank_mask:0xf
	v_mul_f32_e32 v77, v77, v79
	v_mov_b32_dpp v80, v172 row_shr:1 row_mask:0xf bank_mask:0xf
	v_mov_b32_e32 v79, 1.0
	v_fmac_f32_e32 v172, v147, v80
	v_mov_b32_e32 v80, 1.0
	v_mov_b32_e32 v81, v145
	v_mov_b32_dpp v79, v147 row_shr:1 row_mask:0xf bank_mask:0xf
	v_mov_b32_dpp v80, v78 row_shr:2 row_mask:0xf bank_mask:0xf
	v_mov_b32_dpp v81, v168 row_shr:2 row_mask:0xf bank_mask:0xf
	v_mul_f32_e32 v79, v147, v79
	v_fmac_f32_e32 v168, v78, v81
	v_mul_f32_e32 v147, v78, v80
	v_mov_b32_e32 v78, 1.0
	v_mov_b32_e32 v80, v145
	s_waitcnt lgkmcnt(4)
	v_pk_fma_f32 v[162:163], v[86:87], 0, v[84:85] op_sel_hi:[1,0,1]
	v_mov_b32_dpp v78, v76 row_shr:2 row_mask:0xf bank_mask:0xf
	v_mov_b32_dpp v80, v144 row_shr:2 row_mask:0xf bank_mask:0xf
	v_fmac_f32_e32 v144, v76, v80
	v_mul_f32_e32 v169, v76, v78
	v_mov_b32_e32 v76, 1.0
	v_mov_b32_e32 v78, v145
	s_nop 0
	s_nop 0
	s_waitcnt vmcnt(8)
	v_lshlrev_b32_e32 v84, 16, v220
	v_mov_b32_dpp v76, v77 row_shr:2 row_mask:0xf bank_mask:0xf
	v_mul_f32_e32 v170, v77, v76
	v_mov_b32_e32 v76, 1.0
	v_mov_b32_dpp v78, v171 row_shr:2 row_mask:0xf bank_mask:0xf
	v_fmac_f32_e32 v171, v77, v78
	v_mov_b32_dpp v76, v79 row_shr:2 row_mask:0xf bank_mask:0xf
	v_mul_f32_e32 v173, v79, v76
	v_mov_b32_e32 v76, v145
	v_mov_b32_e32 v77, v145
	v_mul_f32_e32 v84, 0xbfb8aa3b, v84
	v_mov_b32_dpp v76, v168 row_shr:4 row_mask:0xf bank_mask:0xf
	v_fmac_f32_e32 v168, v147, v76
	v_mov_b32_e32 v76, v145
	v_mov_b32_dpp v77, v172 row_shr:2 row_mask:0xf bank_mask:0xf
	v_fmac_f32_e32 v172, v79, v77
	v_mov_b32_dpp v76, v144 row_shr:4 row_mask:0xf bank_mask:0xf
	v_fmac_f32_e32 v144, v169, v76
	v_mov_b32_e32 v76, v145
	v_mov_b32_e32 v77, 1.0
	v_exp_f32_e32 v153, v84
	v_mov_b32_dpp v76, v171 row_shr:4 row_mask:0xf bank_mask:0xf
	v_fmac_f32_e32 v171, v170, v76
	v_mov_b32_e32 v76, v145
	v_mov_b32_dpp v77, v147 row_shr:4 row_mask:0xf bank_mask:0xf
	v_mov_b32_e32 v152, v145
	v_mov_b32_dpp v76, v172 row_shr:4 row_mask:0xf bank_mask:0xf
	v_fmac_f32_e32 v172, v173, v76
	v_lshlrev_b32_e32 v76, 16, v218
	v_pk_mul_f32 v[84:85], v[146:147], v[76:77]
	v_mul_f32_e32 v77, 0x3d372713, v76
	v_mul_f32_e32 v77, v77, v76
	v_fmac_f32_e32 v76, v77, v76
	v_mul_f32_e32 v76, 0x3f4c422a, v76
	v_add_f32_e32 v76, v76, v76
	v_mul_f32_e32 v76, 0x3fb8aa3b, v76
	v_exp_f32_e32 v77, v76
	v_add_f32_e32 v76, 1.0, v153
	v_rcp_f32_e32 v76, v76
	v_mov_b32_dpp v152, v168 row_shr:8 row_mask:0xf bank_mask:0xf
	v_add_f32_e32 v77, 1.0, v77
	v_rcp_f32_e32 v77, v77
	v_mov_b32_e32 v153, 1.0
	v_fmac_f32_e32 v168, v85, v152
	v_mov_b32_e32 v79, 1.0
	v_fma_f32 v77, v77, -2.0, 1.0
	v_mov_b32_dpp v153, v85 row_shr:8 row_mask:0xf bank_mask:0xf
	v_add_f32_e32 v152, 1.0, v77
	v_pk_mul_f32 v[84:85], v[84:85], v[152:153]
	v_mov_b32_e32 v77, v162
	v_lshlrev_b32_e32 v80, 16, v219
	v_and_b32_e32 v82, 0xffff0000, v219
	v_and_b32_e32 v167, 0xffff0000, v220
	v_pk_mul_f32 v[76:77], v[76:77], v[84:85]
	v_mov_b32_dpp v79, v169 row_shr:4 row_mask:0xf bank_mask:0xf
	v_and_b32_e32 v78, 0xffff0000, v218
	v_add_f32_e32 v77, v77, v168
	v_mul_f32_e32 v84, 0xbfb8aa3b, v167
	v_mov_b32_e32 v147, v169
	ds_bpermute_b32 v164, v184, v85
	v_mul_f32_e32 v152, v76, v77
	v_mul_f32_e32 v77, v85, v86
	v_exp_f32_e32 v153, v84
	v_pk_mul_f32 v[84:85], v[146:147], v[78:79]
	v_mul_f32_e32 v79, 0x3d372713, v78
	v_mul_f32_e32 v79, v79, v78
	v_fmac_f32_e32 v78, v79, v78
	v_mul_f32_e32 v78, 0x3f4c422a, v78
	v_add_f32_e32 v78, v78, v78
	v_mul_f32_e32 v78, 0x3fb8aa3b, v78
	v_exp_f32_e32 v78, v78
	v_mul_f32_e32 v179, v76, v77
	v_add_f32_e32 v76, 1.0, v153
	v_rcp_f32_e32 v76, v76
	v_add_f32_e32 v77, 1.0, v78
	v_rcp_f32_e32 v77, v77
	v_mov_b32_e32 v79, 1.0
	v_mov_b32_e32 v174, v145
	v_mov_b32_e32 v81, 1.0
	v_fma_f32 v77, v77, -2.0, 1.0
	v_mov_b32_dpp v79, v85 row_shr:8 row_mask:0xf bank_mask:0xf
	v_add_f32_e32 v78, 1.0, v77
	v_mov_b32_dpp v174, v144 row_shr:8 row_mask:0xf bank_mask:0xf
	v_pk_mul_f32 v[78:79], v[84:85], v[78:79]
	v_mov_b32_e32 v77, v163
	v_lshlrev_b32_e32 v177, 16, v221
	v_fmac_f32_e32 v144, v85, v174
	v_pk_mul_f32 v[76:77], v[76:77], v[78:79]
	v_mov_b32_dpp v81, v170 row_shr:4 row_mask:0xf bank_mask:0xf
	v_add_f32_e32 v77, v77, v144
	v_mul_f32_e32 v78, 0xbfb8aa3b, v177
	v_mov_b32_e32 v147, v170
	v_and_b32_e32 v178, 0xffff0000, v221
	ds_bpermute_b32 v165, v184, v79
	v_mul_f32_e32 v84, v76, v77
	v_mul_f32_e32 v77, v79, v87
	v_exp_f32_e32 v85, v78
	v_pk_mul_f32 v[78:79], v[146:147], v[80:81]
	v_mul_f32_e32 v81, 0x3d372713, v80
	v_mul_f32_e32 v81, v81, v80
	v_fmac_f32_e32 v80, v81, v80
	v_mul_f32_e32 v80, 0x3f4c422a, v80
	v_add_f32_e32 v80, v80, v80
	v_mul_f32_e32 v80, 0x3fb8aa3b, v80
	v_exp_f32_e32 v80, v80
	ds_bpermute_b32 v167, v184, v144
	v_mul_f32_e32 v144, v76, v77
	v_add_f32_e32 v76, 1.0, v85
	v_add_f32_e32 v77, 1.0, v80
	v_rcp_f32_e32 v77, v77
	v_rcp_f32_e32 v76, v76
	v_mov_b32_e32 v175, v145
	v_mov_b32_e32 v81, 1.0
	v_fma_f32 v77, v77, -2.0, 1.0
	s_waitcnt lgkmcnt(3)
	v_pk_fma_f32 v[142:143], v[140:141], 0, v[142:143] op_sel_hi:[1,0,1]
	v_mov_b32_dpp v175, v171 row_shr:8 row_mask:0xf bank_mask:0xf
	v_mov_b32_dpp v81, v79 row_shr:8 row_mask:0xf bank_mask:0xf
	v_add_f32_e32 v80, 1.0, v77
	v_fmac_f32_e32 v171, v79, v175
	v_pk_mul_f32 v[78:79], v[78:79], v[80:81]
	v_mov_b32_e32 v77, v142
	v_mov_b32_e32 v83, 1.0
	v_pk_mul_f32 v[76:77], v[76:77], v[78:79]
	v_mul_f32_e32 v81, 0x3d372713, v82
	v_mov_b32_dpp v83, v173 row_shr:4 row_mask:0xf bank_mask:0xf
	v_add_f32_e32 v77, v77, v171
	v_mul_f32_e32 v78, 0xbfb8aa3b, v178
	v_mov_b32_e32 v147, v173
	v_mul_f32_e32 v81, v81, v82
	ds_bpermute_b32 v166, v184, v168
	ds_bpermute_b32 v168, v184, v79
	v_mul_f32_e32 v85, v76, v77
	v_mul_f32_e32 v77, v79, v140
	v_exp_f32_e32 v80, v78
	v_pk_mul_f32 v[78:79], v[146:147], v[82:83]
	v_fmac_f32_e32 v82, v81, v82
	v_mul_f32_e32 v81, 0x3f4c422a, v82
	v_add_f32_e32 v81, v81, v81
	v_mul_f32_e32 v81, 0x3fb8aa3b, v81
	v_exp_f32_e32 v81, v81
	v_mul_f32_e32 v82, v76, v77
	v_add_f32_e32 v76, 1.0, v80
	v_rcp_f32_e32 v76, v76
	v_add_f32_e32 v77, 1.0, v81
	v_rcp_f32_e32 v77, v77
	v_mov_b32_e32 v176, v145
	v_mov_b32_e32 v81, 1.0
	ds_bpermute_b32 v170, v184, v171
	v_fma_f32 v77, v77, -2.0, 1.0
	v_mov_b32_dpp v176, v172 row_shr:8 row_mask:0xf bank_mask:0xf
	v_mov_b32_dpp v81, v79 row_shr:8 row_mask:0xf bank_mask:0xf
	v_add_f32_e32 v80, 1.0, v77
	v_fmac_f32_e32 v172, v79, v176
	v_pk_mul_f32 v[78:79], v[78:79], v[80:81]
	v_mov_b32_e32 v77, v143
	v_pk_mul_f32 v[76:77], v[76:77], v[78:79]
	v_mul_f32_e32 v78, v79, v141
	v_add_f32_e32 v77, v77, v172
	v_mul_f32_e32 v77, v76, v77
	ds_bpermute_b32 v169, v184, v79
	ds_bpermute_b32 v171, v184, v172
	v_mul_f32_e32 v80, v76, v78
	v_cvt_pk_bf16_f32 v76, v152, v84
	v_cvt_pk_bf16_f32 v77, v85, v77
	v_lshl_add_u64 v[84:85], s[74:75], 0, v[132:133]
	s_mov_b32 s54, 0x25d49000
	v_add_co_u32_e32 v78, vcc, s54, v84
	s_mov_b32 s54, 0x27d49000
	s_nop 0
	v_addc_co_u32_e32 v79, vcc, 0, v85, vcc
	global_store_dwordx2 v[78:79], v[76:77], off
	v_add_co_u32_e32 v78, vcc, s54, v84
	v_cvt_pk_bf16_f32 v76, v179, v144
	v_cvt_pk_bf16_f32 v77, v82, v80
	s_nop 1
	v_addc_co_u32_e32 v79, vcc, 0, v85, vcc
	global_store_dwordx2 v[78:79], v[76:77], off
	s_mov_b32 s54, 0x13118000
	v_add_co_u32_e32 v80, vcc, s54, v138
	s_mov_b32 s54, 0x1311c000
	s_nop 0
	v_addc_co_u32_e32 v81, vcc, 0, v139, vcc
	s_nop 0
	v_add_co_u32_e32 v80, vcc, s54, v138
	s_mov_b32 s54, 0x13120000
	s_nop 0
	v_addc_co_u32_e32 v81, vcc, 0, v139, vcc
	s_nop 0
	v_add_co_u32_e32 v80, vcc, s54, v138
	s_mov_b32 s54, 0x13125000
	s_nop 0
	v_addc_co_u32_e32 v81, vcc, 0, v139, vcc
	v_add_co_u32_e32 v152, vcc, s54, v138
	s_nop 0
	s_nop 0
	v_addc_co_u32_e32 v153, vcc, 0, v139, vcc
	s_nop 0
	s_nop 0
	v_add_co_u32_e32 v152, vcc, 0x13128000, v138
	v_mfma_f32_16x16x32_bf16 v[80:83], v[72:75], v[8:11], 0
	s_nop 0
	v_addc_co_u32_e32 v153, vcc, 0, v139, vcc
	s_nop 0
	v_mfma_f32_16x16x32_bf16 v[80:83], v[60:63], v[24:27], v[80:83]
	v_mfma_f32_16x16x32_bf16 v[76:79], v[68:71], v[8:11], 0
	v_mfma_f32_16x16x32_bf16 v[76:79], v[64:67], v[24:27], v[76:79]
	s_nop 5
	v_add_f32_e32 v80, v56, v80
	v_mul_f32_e32 v80, 0xbfb8aa3b, v80
	v_exp_f32_e32 v80, v80
	s_nop 0
	v_add_f32_e32 v80, 1.0, v80
	v_rcp_f32_e32 v80, v80
	s_nop 0
	v_mul_f32_e32 v80, 0xc1000000, v80
	v_mul_f32_e32 v144, v185, v80
	v_add_f32_e32 v147, v144, v144
	v_cmp_nlt_f32_e32 vcc, s93, v147
	s_and_saveexec_b64 s[54:55], vcc
	s_xor_b64 s[54:55], exec, s[54:55]
	v_mul_f32_e32 v80, 0x3fb8aa3b, v147
	v_exp_f32_e32 v80, v80
	s_nop 0
	v_sub_f32_e32 v80, 1.0, v80
	s_andn2_saveexec_b64 s[54:55], s[54:55]
	v_fma_f32 v80, v147, s94, 0.5
	v_fma_f32 v80, v147, v80, 1.0
	v_mul_f32_e64 v80, v80, -v147
	s_or_b64 exec, exec, s[54:55]
	v_add_f32_e32 v81, v57, v81
	v_mul_f32_e32 v81, 0xbfb8aa3b, v81
	v_exp_f32_e32 v81, v81
	s_nop 0
	v_add_f32_e32 v81, 1.0, v81
	v_rcp_f32_e32 v81, v81
	s_nop 0
	v_mul_f32_e32 v81, 0xc1000000, v81
	v_mul_f32_e32 v81, v186, v81
	v_add_f32_e32 v189, v81, v81
	v_cmp_nlt_f32_e32 vcc, s93, v189
	s_and_saveexec_b64 s[54:55], vcc
	s_xor_b64 s[54:55], exec, s[54:55]
	v_mul_f32_e32 v147, 0x3fb8aa3b, v189
	v_exp_f32_e32 v147, v147
	s_nop 0
	v_sub_f32_e32 v147, 1.0, v147
	s_andn2_saveexec_b64 s[54:55], s[54:55]
	v_fma_f32 v147, v189, s94, 0.5
	v_fma_f32 v147, v189, v147, 1.0
	v_mul_f32_e64 v147, v147, -v189
	s_or_b64 exec, exec, s[54:55]
	v_add_f32_e32 v82, v58, v82
	v_mul_f32_e32 v82, 0xbfb8aa3b, v82
	v_exp_f32_e32 v82, v82
	s_nop 0
	v_add_f32_e32 v82, 1.0, v82
	v_rcp_f32_e32 v82, v82
	s_nop 0
	v_mul_f32_e32 v82, 0xc1000000, v82
	v_mul_f32_e32 v82, v187, v82
	v_add_f32_e32 v189, v82, v82
	v_cmp_nlt_f32_e32 vcc, s93, v189
	s_and_saveexec_b64 s[54:55], vcc
	s_xor_b64 s[54:55], exec, s[54:55]
	v_mul_f32_e32 v152, 0x3fb8aa3b, v189
	v_exp_f32_e32 v152, v152
	s_nop 0
	v_sub_f32_e32 v190, 1.0, v152
	s_andn2_saveexec_b64 s[54:55], s[54:55]
	v_fma_f32 v152, v189, s94, 0.5
	v_fma_f32 v152, v189, v152, 1.0
	v_mul_f32_e64 v190, v152, -v189
	s_or_b64 exec, exec, s[54:55]
	v_add_f32_e32 v83, v59, v83
	v_mul_f32_e32 v83, 0xbfb8aa3b, v83
	v_exp_f32_e32 v83, v83
	s_nop 0
	v_add_f32_e32 v83, 1.0, v83
	v_rcp_f32_e32 v83, v83
	s_nop 0
	v_mul_f32_e32 v83, 0xc1000000, v83
	v_mul_f32_e32 v83, v188, v83
	v_add_f32_e32 v191, v83, v83
	v_cmp_nlt_f32_e32 vcc, s93, v191
	s_and_saveexec_b64 s[54:55], vcc
	s_xor_b64 s[54:55], exec, s[54:55]
	v_mul_f32_e32 v152, 0x3fb8aa3b, v191
	v_exp_f32_e32 v152, v152
	s_nop 0
	v_sub_f32_e32 v189, 1.0, v152
	s_andn2_saveexec_b64 s[54:55], s[54:55]
	v_fma_f32 v152, v191, s94, 0.5
	v_fma_f32 v152, v191, v152, 1.0
	v_mul_f32_e64 v189, v152, -v191
	s_or_b64 exec, exec, s[54:55]
	v_add_f32_e32 v78, v34, v78
	v_mul_f32_e32 v78, 0xbfb8aa3b, v78
	s_nop 0
	s_nop 0
	s_waitcnt vmcnt(9)
	v_mov_b32_dpp v222, v228 row_shr:3 row_mask:0xf bank_mask:0xf
	v_mov_b32_dpp v223, v229 row_shr:3 row_mask:0xf bank_mask:0xf
	v_mov_b32_dpp v224, v228 row_shr:2 row_mask:0xf bank_mask:0xf
	v_mov_b32_dpp v225, v229 row_shr:2 row_mask:0xf bank_mask:0xf
	v_mov_b32_dpp v226, v228 row_shr:1 row_mask:0xf bank_mask:0xf
	v_mov_b32_dpp v227, v229 row_shr:1 row_mask:0xf bank_mask:0xf
	v_cndmask_b32_e64 v181, v223, 0, s[42:43]
	v_cndmask_b32_e64 v153, v222, 0, s[42:43]
	v_exp_f32_e32 v78, v78
	v_lshlrev_b32_e32 v152, 16, v153
	v_and_b32_e32 v153, 0xffff0000, v153
	v_lshlrev_b32_e32 v180, 16, v181
	v_and_b32_e32 v181, 0xffff0000, v181
	s_nop 0
	s_nop 0
	v_cndmask_b32_e64 v191, v225, 0, s[44:45]
	v_cndmask_b32_e64 v177, v224, 0, s[44:45]
	v_pk_fma_f32 v[180:181], v[50:51], v[180:181], v[54:55]
	v_pk_fma_f32 v[152:153], v[48:49], v[152:153], v[52:53]
	v_lshlrev_b32_e32 v176, 16, v177
	v_and_b32_e32 v177, 0xffff0000, v177
	v_lshlrev_b32_e32 v192, 16, v191
	v_and_b32_e32 v193, 0xffff0000, v191
	v_pk_fma_f32 v[152:153], v[44:45], v[176:177], v[152:153]
	v_pk_fma_f32 v[176:177], v[46:47], v[192:193], v[180:181]
	s_nop 0
	s_nop 0
	v_cndmask_b32_e64 v181, v227, 0, s[46:47]
	v_cndmask_b32_e64 v179, v226, 0, s[46:47]
	v_lshlrev_b32_e32 v178, 16, v179
	v_and_b32_e32 v179, 0xffff0000, v179
	v_add_f32_e32 v78, 1.0, v78
	v_add_f32_e32 v79, v35, v79
	v_add_f32_e32 v77, v33, v77
	v_pk_fma_f32 v[152:153], v[40:41], v[178:179], v[152:153]
	s_nop 0
	s_nop 0
	v_mov_b32_dpp v234, v228 row_shl:13 row_mask:0xf bank_mask:0xf
	v_mov_b32_dpp v235, v229 row_shl:13 row_mask:0xf bank_mask:0xf
	v_mov_b32_dpp v236, v228 row_shl:14 row_mask:0xf bank_mask:0xf
	v_mov_b32_dpp v237, v229 row_shl:14 row_mask:0xf bank_mask:0xf
	v_mov_b32_dpp v238, v228 row_shl:15 row_mask:0xf bank_mask:0xf
	v_mov_b32_dpp v239, v229 row_shl:15 row_mask:0xf bank_mask:0xf
	v_cndmask_b32_e64 v179, v228, 0, s[64:65]
	v_rcp_f32_e32 v78, v78
	v_sqrt_f32_e32 v182, v190
	v_mul_f32_e32 v79, 0xbfb8aa3b, v79
	v_mul_f32_e32 v77, 0xbfb8aa3b, v77
	v_lshlrev_b32_e32 v180, 16, v181
	v_and_b32_e32 v181, 0xffff0000, v181
	v_exp_f32_e32 v79, v79
	v_exp_f32_e32 v77, v77
	v_pk_fma_f32 v[176:177], v[42:43], v[180:181], v[176:177]
	v_cndmask_b32_e64 v181, v229, 0, s[64:65]
	v_lshlrev_b32_e32 v180, 16, v181
	v_and_b32_e32 v181, 0xffff0000, v181
	v_add_f32_e32 v76, v32, v76
	v_pk_fma_f32 v[176:177], v[38:39], v[180:181], v[176:177]
	v_mul_f32_e32 v78, v78, v182
	v_mul_f32_e32 v76, 0xbfb8aa3b, v76
	v_lshlrev_b32_e32 v178, 16, v179
	v_and_b32_e32 v179, 0xffff0000, v179
	v_mul_f32_e32 v176, v176, v78
	v_add_f32_e32 v78, 1.0, v79
	v_add_f32_e32 v77, 1.0, v77
	v_exp_f32_e32 v76, v76
	v_pk_fma_f32 v[152:153], v[36:37], v[178:179], v[152:153]
	v_rcp_f32_e32 v178, v78
	v_rcp_f32_e32 v77, v77
	v_sqrt_f32_e32 v78, v147
	v_add_f32_e32 v76, 1.0, v76
	v_rcp_f32_e32 v76, v76
	v_mul_f32_e32 v79, 0x3fb8aa3b, v83
	v_mul_f32_e32 v77, v77, v78
	v_sqrt_f32_e32 v78, v80
	v_mul_f32_e32 v179, v153, v77
	v_mul_f32_e32 v77, 0x3fb8aa3b, v82
	s_waitcnt lgkmcnt(6)
	v_pk_mul_f32 v[82:83], v[86:87], v[164:165]
	v_sqrt_f32_e32 v86, v189
	v_mul_f32_e32 v87, 0x3fb8aa3b, v144
	v_mul_f32_e32 v76, v76, v78
	v_exp_f32_e32 v87, v87
	v_exp_f32_e32 v147, v79
	v_exp_f32_e32 v153, v77
	v_mul_f32_e32 v180, v152, v76
	v_mul_f32_e32 v76, 0x3fb8aa3b, v81
	v_exp_f32_e32 v152, v76
	v_mul_f32_e32 v86, v178, v86
	s_waitcnt lgkmcnt(1)
	v_pk_mul_f32 v[78:79], v[140:141], v[168:169]
	s_waitcnt lgkmcnt(0)
	v_pk_fma_f32 v[76:77], v[142:143], v[168:169], v[170:171]
	v_mul_f32_e32 v144, v177, v86
	v_mov_b32_e32 v86, 1.0
	v_mov_b32_e32 v140, v145
	v_mov_b32_e32 v141, v145
	v_mov_b32_e32 v142, v145
	v_mov_b32_dpp v86, v87 row_shr:1 row_mask:0xf bank_mask:0xf
	v_mov_b32_dpp v140, v180 row_shr:1 row_mask:0xf bank_mask:0xf
	v_mov_b32_dpp v141, v176 row_shr:1 row_mask:0xf bank_mask:0xf
	v_mov_b32_dpp v142, v144 row_shr:1 row_mask:0xf bank_mask:0xf
	v_fmac_f32_e32 v180, v87, v140
	v_mul_f32_e32 v86, v87, v86
	v_mov_b32_e32 v87, 1.0
	v_mov_b32_e32 v140, v145
	v_fmac_f32_e32 v176, v153, v141
	v_mov_b32_e32 v141, 1.0
	v_fmac_f32_e32 v144, v147, v142
	v_mov_b32_e32 v142, 1.0
	v_mov_b32_e32 v143, v145
	v_mov_b32_dpp v87, v152 row_shr:1 row_mask:0xf bank_mask:0xf
	v_mov_b32_dpp v140, v179 row_shr:1 row_mask:0xf bank_mask:0xf
	v_mov_b32_dpp v141, v147 row_shr:1 row_mask:0xf bank_mask:0xf
	v_mov_b32_dpp v142, v86 row_shr:2 row_mask:0xf bank_mask:0xf
	v_mov_b32_dpp v143, v180 row_shr:2 row_mask:0xf bank_mask:0xf
	v_fmac_f32_e32 v179, v152, v140
	v_mul_f32_e32 v87, v152, v87
	v_mov_b32_e32 v140, 1.0
	v_mul_f32_e32 v141, v147, v141
	v_fmac_f32_e32 v180, v86, v143
	v_mul_f32_e32 v147, v86, v142
	v_mov_b32_e32 v86, 1.0
	v_mov_b32_dpp v140, v153 row_shr:1 row_mask:0xf bank_mask:0xf
	v_mul_f32_e32 v140, v153, v140
	v_mov_b32_dpp v86, v87 row_shr:2 row_mask:0xf bank_mask:0xf
	v_mul_f32_e32 v168, v87, v86
	v_mov_b32_e32 v86, 1.0
	v_mov_b32_e32 v142, v145
	v_pk_fma_f32 v[80:81], v[162:163], v[164:165], v[166:167]
	v_mov_b32_dpp v86, v140 row_shr:2 row_mask:0xf bank_mask:0xf
	v_mul_f32_e32 v169, v140, v86
	v_mov_b32_e32 v86, 1.0
	v_mov_b32_dpp v142, v179 row_shr:2 row_mask:0xf bank_mask:0xf
	v_fmac_f32_e32 v179, v87, v142
	v_mov_b32_dpp v86, v141 row_shr:2 row_mask:0xf bank_mask:0xf
	v_mul_f32_e32 v170, v141, v86
	v_mov_b32_e32 v86, v145
	v_mov_b32_e32 v87, v145
	v_mov_b32_e32 v163, v145
	v_mov_b32_dpp v86, v180 row_shr:4 row_mask:0xf bank_mask:0xf
	v_fmac_f32_e32 v180, v147, v86
	v_mov_b32_e32 v86, v145
	v_mov_b32_dpp v87, v176 row_shr:2 row_mask:0xf bank_mask:0xf
	v_fmac_f32_e32 v176, v140, v87
	v_mov_b32_dpp v86, v179 row_shr:4 row_mask:0xf bank_mask:0xf
	v_mov_b32_e32 v87, v145
	v_fmac_f32_e32 v179, v168, v86
	v_mov_b32_e32 v86, v145
	v_mov_b32_dpp v87, v144 row_shr:2 row_mask:0xf bank_mask:0xf
	v_fmac_f32_e32 v144, v141, v87
	v_mov_b32_dpp v86, v176 row_shr:4 row_mask:0xf bank_mask:0xf
	v_fmac_f32_e32 v176, v169, v86
	v_mov_b32_e32 v86, v145
	v_mov_b32_e32 v87, 1.0
	s_nop 0
	s_nop 0
	s_waitcnt vmcnt(7)
	v_lshlrev_b32_e32 v140, 16, v232
	v_mov_b32_dpp v86, v144 row_shr:4 row_mask:0xf bank_mask:0xf
	v_mov_b32_dpp v87, v147 row_shr:4 row_mask:0xf bank_mask:0xf
	v_fmac_f32_e32 v144, v170, v86
	v_lshlrev_b32_e32 v86, 16, v230
	v_mul_f32_e32 v140, 0xbfb8aa3b, v140
	v_exp_f32_e32 v162, v140
	v_pk_mul_f32 v[140:141], v[146:147], v[86:87]
	v_mul_f32_e32 v87, 0x3d372713, v86
	v_mul_f32_e32 v87, v87, v86
	v_fmac_f32_e32 v86, v87, v86
	v_mul_f32_e32 v86, 0x3f4c422a, v86
	v_add_f32_e32 v86, v86, v86
	v_mul_f32_e32 v86, 0x3fb8aa3b, v86
	v_exp_f32_e32 v86, v86
	v_add_f32_e32 v87, 1.0, v162
	v_rcp_f32_e32 v162, v87
	v_mov_b32_e32 v87, 1.0
	v_add_f32_e32 v86, 1.0, v86
	v_rcp_f32_e32 v86, v86
	v_mov_b32_e32 v143, 1.0
	v_mov_b32_dpp v163, v180 row_shr:8 row_mask:0xf bank_mask:0xf
	v_mov_b32_dpp v87, v141 row_shr:8 row_mask:0xf bank_mask:0xf
	v_fma_f32 v86, v86, -2.0, 1.0
	v_add_f32_e32 v86, 1.0, v86
	v_mov_b32_dpp v143, v168 row_shr:4 row_mask:0xf bank_mask:0xf
	v_and_b32_e32 v142, 0xffff0000, v230
	v_fmac_f32_e32 v180, v141, v163
	v_pk_mul_f32 v[166:167], v[140:141], v[86:87]
	v_mov_b32_e32 v163, v80
	v_mov_b32_e32 v147, v168
	ds_bpermute_b32 v86, v184, v167
	v_mul_f32_e32 v87, v82, v167
	v_pk_mul_f32 v[162:163], v[162:163], v[166:167]
	v_pk_mul_f32 v[166:167], v[146:147], v[142:143]
	v_mul_f32_e32 v143, 0x3d372713, v142
	v_mul_f32_e32 v143, v143, v142
	v_fmac_f32_e32 v142, v143, v142
	v_and_b32_e32 v172, 0xffff0000, v232
	v_add_f32_e32 v141, v163, v180
	v_mul_f32_e32 v142, 0x3f4c422a, v142
	v_lshlrev_b32_e32 v152, 16, v231
	v_and_b32_e32 v164, 0xffff0000, v231
	v_mul_f32_e32 v175, v162, v141
	v_mul_f32_e32 v141, 0xbfb8aa3b, v172
	v_add_f32_e32 v142, v142, v142
	v_exp_f32_e32 v141, v141
	v_mul_f32_e32 v142, 0x3fb8aa3b, v142
	v_exp_f32_e32 v143, v142
	v_mul_f32_e32 v168, v162, v87
	v_add_f32_e32 v87, 1.0, v141
	v_rcp_f32_e32 v142, v87
	v_add_f32_e32 v87, 1.0, v143
	v_rcp_f32_e32 v87, v87
	v_mov_b32_e32 v163, 1.0
	v_mov_b32_e32 v153, 1.0
	v_mov_b32_e32 v143, v81
	v_fma_f32 v87, v87, -2.0, 1.0
	v_mov_b32_dpp v163, v167 row_shr:8 row_mask:0xf bank_mask:0xf
	v_add_f32_e32 v162, 1.0, v87
	v_mov_b32_dpp v153, v169 row_shr:4 row_mask:0xf bank_mask:0xf
	v_pk_mul_f32 v[162:163], v[166:167], v[162:163]
	v_mov_b32_e32 v147, v169
	v_mov_b32_e32 v171, v145
	ds_bpermute_b32 v87, v184, v163
	v_mul_f32_e32 v166, v83, v163
	v_pk_mul_f32 v[142:143], v[142:143], v[162:163]
	v_pk_mul_f32 v[162:163], v[146:147], v[152:153]
	v_mul_f32_e32 v147, 0x3d372713, v152
	v_mov_b32_dpp v171, v179 row_shr:8 row_mask:0xf bank_mask:0xf
	v_mul_f32_e32 v147, v147, v152
	v_fmac_f32_e32 v179, v167, v171
	v_fmac_f32_e32 v152, v147, v152
	v_lshlrev_b32_e32 v174, 16, v233
	v_add_f32_e32 v143, v143, v179
	v_mul_f32_e32 v147, 0x3f4c422a, v152
	v_mul_f32_e32 v171, v142, v143
	v_mul_f32_e32 v143, 0xbfb8aa3b, v174
	v_add_f32_e32 v147, v147, v147
	v_exp_f32_e32 v143, v143
	v_mul_f32_e32 v147, 0x3fb8aa3b, v147
	v_exp_f32_e32 v147, v147
	v_mul_f32_e32 v169, v142, v166
	v_add_f32_e32 v142, 1.0, v143
	v_rcp_f32_e32 v152, v142
	v_add_f32_e32 v142, 1.0, v147
	v_rcp_f32_e32 v142, v142
	v_mov_b32_e32 v143, 1.0
	v_mov_b32_e32 v177, v145
	v_mov_b32_e32 v153, v76
	v_fma_f32 v142, v142, -2.0, 1.0
	v_mov_b32_dpp v143, v163 row_shr:8 row_mask:0xf bank_mask:0xf
	v_add_f32_e32 v142, 1.0, v142
	v_mov_b32_dpp v177, v176 row_shr:8 row_mask:0xf bank_mask:0xf
	v_pk_mul_f32 v[166:167], v[162:163], v[142:143]
	v_fmac_f32_e32 v176, v163, v177
	v_pk_mul_f32 v[152:153], v[152:153], v[166:167]
	v_and_b32_e32 v173, 0xffff0000, v233
	v_add_f32_e32 v147, v153, v176
	v_mov_b32_e32 v165, 1.0
	v_mul_f32_e32 v172, v152, v147
	v_mul_f32_e32 v147, 0xbfb8aa3b, v173
	v_mov_b32_dpp v165, v170 row_shr:4 row_mask:0xf bank_mask:0xf
	v_exp_f32_e32 v153, v147
	v_mov_b32_e32 v147, v170
	ds_bpermute_b32 v142, v184, v167
	v_mul_f32_e32 v143, v78, v167
	v_pk_mul_f32 v[166:167], v[146:147], v[164:165]
	v_mul_f32_e32 v147, 0x3d372713, v164
	v_mul_f32_e32 v147, v147, v164
	v_fmac_f32_e32 v164, v147, v164
	v_mul_f32_e32 v147, 0x3f4c422a, v164
	v_add_f32_e32 v147, v147, v147
	v_mul_f32_e32 v147, 0x3fb8aa3b, v147
	v_exp_f32_e32 v147, v147
	v_mul_f32_e32 v170, v152, v143
	v_add_f32_e32 v143, 1.0, v153
	v_rcp_f32_e32 v152, v143
	v_add_f32_e32 v143, 1.0, v147
	v_rcp_f32_e32 v143, v143
	v_mov_b32_e32 v178, v145
	v_mov_b32_e32 v165, 1.0
	ds_bpermute_b32 v140, v184, v180
	v_fma_f32 v143, v143, -2.0, 1.0
	v_mov_b32_dpp v178, v144 row_shr:8 row_mask:0xf bank_mask:0xf
	v_mov_b32_dpp v165, v167 row_shr:8 row_mask:0xf bank_mask:0xf
	v_add_f32_e32 v164, 1.0, v143
	v_fmac_f32_e32 v144, v167, v178
	v_pk_mul_f32 v[164:165], v[166:167], v[164:165]
	ds_bpermute_b32 v141, v184, v179
	ds_bpermute_b32 v162, v184, v176
	ds_bpermute_b32 v143, v184, v165
	ds_bpermute_b32 v163, v184, v144
	v_mov_b32_e32 v153, v77
	s_mov_b32 s54, 0x25d51000
	v_pk_mul_f32 v[152:153], v[152:153], v[164:165]
	v_add_co_u32_e32 v164, vcc, s54, v84
	v_mul_f32_e32 v147, v79, v165
	v_add_f32_e32 v144, v153, v144
	v_addc_co_u32_e32 v165, vcc, 0, v85, vcc
	s_mov_b32 s54, 0x27d51000
	v_mul_f32_e32 v144, v152, v144
	v_mul_f32_e32 v147, v152, v147
	v_cvt_pk_bf16_f32 v152, v175, v171
	v_cvt_pk_bf16_f32 v153, v172, v144
	global_store_dwordx2 v[164:165], v[152:153], off
	v_add_co_u32_e32 v164, vcc, s54, v84
	v_cvt_pk_bf16_f32 v152, v168, v169
	v_cvt_pk_bf16_f32 v153, v170, v147
	s_nop 1
	v_addc_co_u32_e32 v165, vcc, 0, v85, vcc
	global_store_dwordx2 v[164:165], v[152:153], off
	s_mov_b32 s54, 0x1315a000
	v_add_co_u32_e32 v152, vcc, s54, v138
	s_mov_b32 s54, 0x1315e000
	s_nop 0
	v_addc_co_u32_e32 v153, vcc, 0, v139, vcc
	v_add_co_u32_e32 v164, vcc, s54, v138
	s_mov_b32 s54, 0x13162000
	s_nop 0
	v_addc_co_u32_e32 v165, vcc, 0, v139, vcc
	v_add_co_u32_e32 v166, vcc, s54, v138
	s_mov_b32 s54, 0x13167000
	s_nop 0
	v_addc_co_u32_e32 v167, vcc, 0, v139, vcc
	v_add_co_u32_e32 v174, vcc, s54, v138
	v_mfma_f32_16x16x32_bf16 v[72:75], v[72:75], v[12:15], 0
	s_nop 0
	v_addc_co_u32_e32 v175, vcc, 0, v139, vcc
	s_nop 0
	s_nop 0
	s_nop 0
	s_nop 0
	s_nop 0
	v_add_co_u32_e32 v138, vcc, 0x1316a000, v138
	v_mfma_f32_16x16x32_bf16 v[72:75], v[60:63], v[28:31], v[72:75]
	s_nop 0
	v_addc_co_u32_e32 v139, vcc, 0, v139, vcc
	s_nop 0
	s_nop 0
	s_nop 0
	s_nop 2
	v_add_f32_e32 v56, v56, v72
	v_mul_f32_e32 v56, 0xbfb8aa3b, v56
	v_exp_f32_e32 v56, v56
	v_mfma_f32_16x16x32_bf16 v[60:63], v[68:71], v[12:15], 0
	v_add_f32_e32 v56, 1.0, v56
	v_rcp_f32_e32 v56, v56
	v_mfma_f32_16x16x32_bf16 v[60:63], v[64:67], v[28:31], v[60:63]
	v_mul_f32_e32 v56, 0xc1000000, v56
	v_mul_f32_e32 v56, v185, v56
	v_add_f32_e32 v65, v56, v56
	v_cmp_nlt_f32_e32 vcc, s93, v65
	s_and_saveexec_b64 s[54:55], vcc
	s_xor_b64 s[54:55], exec, s[54:55]
	v_mul_f32_e32 v64, 0x3fb8aa3b, v65
	v_exp_f32_e32 v64, v64
	s_nop 0
	v_sub_f32_e32 v64, 1.0, v64
	s_andn2_saveexec_b64 s[54:55], s[54:55]
	v_fma_f32 v64, v65, s94, 0.5
	v_fma_f32 v64, v65, v64, 1.0
	v_mul_f32_e64 v64, v64, -v65
	s_or_b64 exec, exec, s[54:55]
	v_add_f32_e32 v57, v57, v73
	v_mul_f32_e32 v57, 0xbfb8aa3b, v57
	v_exp_f32_e32 v57, v57
	s_nop 0
	v_add_f32_e32 v57, 1.0, v57
	v_rcp_f32_e32 v57, v57
	s_nop 0
	v_mul_f32_e32 v57, 0xc1000000, v57
	v_mul_f32_e32 v57, v186, v57
	v_add_f32_e32 v66, v57, v57
	v_cmp_nlt_f32_e32 vcc, s93, v66
	s_and_saveexec_b64 s[54:55], vcc
	s_xor_b64 s[54:55], exec, s[54:55]
	v_mul_f32_e32 v65, 0x3fb8aa3b, v66
	v_exp_f32_e32 v65, v65
	s_nop 0
	v_sub_f32_e32 v65, 1.0, v65
	s_andn2_saveexec_b64 s[54:55], s[54:55]
	v_fma_f32 v65, v66, s94, 0.5
	v_fma_f32 v65, v66, v65, 1.0
	v_mul_f32_e64 v65, v65, -v66
	s_or_b64 exec, exec, s[54:55]
	v_add_f32_e32 v58, v58, v74
	v_mul_f32_e32 v58, 0xbfb8aa3b, v58
	v_exp_f32_e32 v58, v58
	s_nop 0
	v_add_f32_e32 v58, 1.0, v58
	v_rcp_f32_e32 v58, v58
	s_nop 0
	v_mul_f32_e32 v58, 0xc1000000, v58
	v_mul_f32_e32 v58, v187, v58
	v_add_f32_e32 v67, v58, v58
	v_cmp_nlt_f32_e32 vcc, s93, v67
	s_and_saveexec_b64 s[54:55], vcc
	s_xor_b64 s[54:55], exec, s[54:55]
	v_mul_f32_e32 v66, 0x3fb8aa3b, v67
	v_exp_f32_e32 v66, v66
	s_nop 0
	v_sub_f32_e32 v66, 1.0, v66
	s_andn2_saveexec_b64 s[54:55], s[54:55]
	v_fma_f32 v66, v67, s94, 0.5
	v_fma_f32 v66, v67, v66, 1.0
	v_mul_f32_e64 v66, v66, -v67
	s_or_b64 exec, exec, s[54:55]
	v_add_f32_e32 v59, v59, v75
	v_mul_f32_e32 v59, 0xbfb8aa3b, v59
	v_exp_f32_e32 v59, v59
	s_nop 0
	v_add_f32_e32 v59, 1.0, v59
	v_rcp_f32_e32 v59, v59
	s_nop 0
	v_mul_f32_e32 v59, 0xc1000000, v59
	v_mul_f32_e32 v67, v188, v59
	v_add_f32_e32 v68, v67, v67
	v_cmp_nlt_f32_e32 vcc, s93, v68
	s_and_saveexec_b64 s[54:55], vcc
	s_xor_b64 s[54:55], exec, s[54:55]
	v_mul_f32_e32 v59, 0x3fb8aa3b, v68
	v_exp_f32_e32 v59, v59
	s_nop 0
	v_sub_f32_e32 v59, 1.0, v59
	s_andn2_saveexec_b64 s[54:55], s[54:55]
	v_fma_f32 v59, v68, s94, 0.5
	v_fma_f32 v59, v68, v59, 1.0
	v_mul_f32_e64 v59, v59, -v68
	s_or_b64 exec, exec, s[54:55]
	v_add_f32_e32 v34, v34, v62
	s_nop 0
	s_nop 0
	s_waitcnt vmcnt(8)
	v_mov_b32_dpp v234, v242 row_shr:3 row_mask:0xf bank_mask:0xf
	v_mov_b32_dpp v235, v243 row_shr:3 row_mask:0xf bank_mask:0xf
	v_mov_b32_dpp v236, v242 row_shr:2 row_mask:0xf bank_mask:0xf
	v_mov_b32_dpp v237, v243 row_shr:2 row_mask:0xf bank_mask:0xf
	v_mov_b32_dpp v238, v242 row_shr:1 row_mask:0xf bank_mask:0xf
	v_mov_b32_dpp v239, v243 row_shr:1 row_mask:0xf bank_mask:0xf
	v_cndmask_b32_e64 v69, v234, 0, s[48:49]
	v_mul_f32_e32 v34, 0xbfb8aa3b, v34
	v_lshlrev_b32_e32 v68, 16, v69
	v_and_b32_e32 v69, 0xffff0000, v69
	v_exp_f32_e32 v34, v34
	v_cndmask_b32_e64 v71, v235, 0, s[48:49]
	v_pk_fma_f32 v[48:49], v[48:49], v[68:69], v[52:53]
	s_nop 0
	s_nop 0
	v_cndmask_b32_e64 v53, v236, 0, s[50:51]
	v_lshlrev_b32_e32 v70, 16, v71
	v_and_b32_e32 v71, 0xffff0000, v71
	v_lshlrev_b32_e32 v52, 16, v53
	v_and_b32_e32 v53, 0xffff0000, v53
	v_pk_fma_f32 v[50:51], v[50:51], v[70:71], v[54:55]
	v_cndmask_b32_e64 v55, v237, 0, s[50:51]
	v_pk_fma_f32 v[44:45], v[44:45], v[52:53], v[48:49]
	s_nop 0
	s_nop 0
	v_cndmask_b32_e64 v49, v238, 0, s[52:53]
	v_lshlrev_b32_e32 v54, 16, v55
	v_and_b32_e32 v55, 0xffff0000, v55
	v_lshlrev_b32_e32 v48, 16, v49
	v_and_b32_e32 v49, 0xffff0000, v49
	v_add_f32_e32 v34, 1.0, v34
	v_add_f32_e32 v35, v35, v63
	v_add_f32_e32 v33, v33, v61
	v_pk_fma_f32 v[46:47], v[46:47], v[54:55], v[50:51]
	v_cndmask_b32_e64 v51, v239, 0, s[52:53]
	v_pk_fma_f32 v[40:41], v[40:41], v[48:49], v[44:45]
	v_rcp_f32_e32 v34, v34
	v_sqrt_f32_e32 v48, v66
	v_mul_f32_e32 v35, 0xbfb8aa3b, v35
	v_mul_f32_e32 v33, 0xbfb8aa3b, v33
	v_lshlrev_b32_e32 v50, 16, v51
	v_and_b32_e32 v51, 0xffff0000, v51
	v_exp_f32_e32 v35, v35
	v_exp_f32_e32 v33, v33
	v_pk_fma_f32 v[42:43], v[42:43], v[50:51], v[46:47]
	s_nop 0
	s_nop 0
	v_cndmask_b32_e64 v47, v243, 0, s[64:65]
	v_cndmask_b32_e64 v45, v242, 0, s[64:65]
	v_lshlrev_b32_e32 v44, 16, v45
	v_and_b32_e32 v45, 0xffff0000, v45
	v_lshlrev_b32_e32 v46, 16, v47
	v_and_b32_e32 v47, 0xffff0000, v47
	v_add_f32_e32 v32, v32, v60
	v_pk_fma_f32 v[36:37], v[36:37], v[44:45], v[40:41]
	v_pk_fma_f32 v[40:41], v[38:39], v[46:47], v[42:43]
	v_mul_f32_e32 v34, v34, v48
	v_mul_f32_e32 v32, 0xbfb8aa3b, v32
	v_mul_f32_e32 v54, v40, v34
	v_add_f32_e32 v34, 1.0, v35
	v_add_f32_e32 v33, 1.0, v33
	v_exp_f32_e32 v32, v32
	v_rcp_f32_e32 v40, v34
	v_rcp_f32_e32 v33, v33
	v_sqrt_f32_e32 v34, v65
	v_add_f32_e32 v32, 1.0, v32
	v_rcp_f32_e32 v32, v32
	v_sqrt_f32_e32 v45, v59
	v_mul_f32_e32 v33, v33, v34
	v_sqrt_f32_e32 v34, v64
	v_mul_f32_e32 v46, 0x3fb8aa3b, v56
	v_mul_f32_e32 v55, v37, v33
	v_mul_f32_e32 v33, 0x3fb8aa3b, v58
	v_mul_f32_e32 v32, v32, v34
	v_mul_f32_e32 v58, v36, v32
	v_mul_f32_e32 v32, 0x3fb8aa3b, v57
	v_exp_f32_e32 v46, v46
	v_exp_f32_e32 v44, v32
	v_mul_f32_e32 v40, v40, v45
	v_mul_f32_e32 v56, v41, v40
	v_mov_b32_e32 v41, v145
	v_exp_f32_e32 v43, v33
	v_mul_f32_e32 v35, 0x3fb8aa3b, v67
	v_mov_b32_dpp v41, v58 row_shr:1 row_mask:0xf bank_mask:0xf
	v_fmac_f32_e32 v58, v46, v41
	v_mov_b32_e32 v41, 1.0
	v_mov_b32_e32 v45, v145
	v_exp_f32_e32 v42, v35
	v_mov_b32_dpp v41, v44 row_shr:1 row_mask:0xf bank_mask:0xf
	v_mov_b32_dpp v45, v55 row_shr:1 row_mask:0xf bank_mask:0xf
	v_fmac_f32_e32 v55, v44, v45
	v_mul_f32_e32 v41, v44, v41
	v_mov_b32_e32 v44, 1.0
	v_mov_b32_e32 v45, v145
	v_mov_b32_e32 v40, 1.0
	v_mov_b32_dpp v44, v43 row_shr:1 row_mask:0xf bank_mask:0xf
	v_mov_b32_dpp v45, v54 row_shr:1 row_mask:0xf bank_mask:0xf
	v_fmac_f32_e32 v54, v43, v45
	v_mul_f32_e32 v43, v43, v44
	v_mov_b32_e32 v44, 1.0
	v_mov_b32_e32 v45, v145
	v_mov_b32_dpp v40, v46 row_shr:1 row_mask:0xf bank_mask:0xf
	v_mov_b32_dpp v44, v42 row_shr:1 row_mask:0xf bank_mask:0xf
	v_mov_b32_dpp v45, v56 row_shr:1 row_mask:0xf bank_mask:0xf
	v_mul_f32_e32 v40, v46, v40
	v_fmac_f32_e32 v56, v42, v45
	v_mul_f32_e32 v42, v42, v44
	v_mov_b32_e32 v44, 1.0
	v_mov_b32_e32 v45, v145
	v_mov_b32_e32 v51, v145
	v_mov_b32_dpp v44, v40 row_shr:2 row_mask:0xf bank_mask:0xf
	v_mov_b32_dpp v45, v58 row_shr:2 row_mask:0xf bank_mask:0xf
	v_fmac_f32_e32 v58, v40, v45
	v_mul_f32_e32 v147, v40, v44
	v_mov_b32_e32 v40, 1.0
	v_mov_b32_e32 v44, v145
	s_waitcnt lgkmcnt(3)
	v_pk_fma_f32 v[38:39], v[80:81], v[86:87], v[140:141]
	v_mov_b32_dpp v40, v41 row_shr:2 row_mask:0xf bank_mask:0xf
	v_mul_f32_e32 v57, v41, v40
	v_mov_b32_e32 v40, 1.0
	v_mov_b32_dpp v44, v55 row_shr:2 row_mask:0xf bank_mask:0xf
	v_fmac_f32_e32 v55, v41, v44
	v_mov_b32_dpp v40, v43 row_shr:2 row_mask:0xf bank_mask:0xf
	v_mul_f32_e32 v59, v43, v40
	v_mov_b32_e32 v40, 1.0
	v_mov_b32_e32 v41, v145
	v_mov_b32_e32 v45, 1.0
	v_mov_b32_dpp v40, v42 row_shr:2 row_mask:0xf bank_mask:0xf
	v_mul_f32_e32 v60, v42, v40
	v_mov_b32_e32 v40, v145
	v_mov_b32_dpp v41, v54 row_shr:2 row_mask:0xf bank_mask:0xf
	v_fmac_f32_e32 v54, v43, v41
	v_mov_b32_dpp v40, v58 row_shr:4 row_mask:0xf bank_mask:0xf
	v_fmac_f32_e32 v58, v147, v40
	v_mov_b32_e32 v40, v145
	v_mov_b32_e32 v41, v145
	v_mov_b32_dpp v51, v58 row_shr:8 row_mask:0xf bank_mask:0xf
	v_mov_b32_dpp v40, v55 row_shr:4 row_mask:0xf bank_mask:0xf
	v_fmac_f32_e32 v55, v57, v40
	v_mov_b32_e32 v40, v145
	v_mov_b32_dpp v41, v56 row_shr:2 row_mask:0xf bank_mask:0xf
	v_fmac_f32_e32 v56, v42, v41
	v_mov_b32_dpp v40, v54 row_shr:4 row_mask:0xf bank_mask:0xf
	v_fmac_f32_e32 v54, v59, v40
	v_mov_b32_e32 v40, v145
	v_mov_b32_e32 v41, 1.0
	s_nop 0
	s_nop 0
	s_waitcnt vmcnt(6)
	v_lshlrev_b32_e32 v42, 16, v246
	v_mov_b32_dpp v40, v56 row_shr:4 row_mask:0xf bank_mask:0xf
	v_mov_b32_dpp v41, v147 row_shr:4 row_mask:0xf bank_mask:0xf
	v_fmac_f32_e32 v56, v60, v40
	v_lshlrev_b32_e32 v40, 16, v244
	v_mul_f32_e32 v42, 0xbfb8aa3b, v42
	v_exp_f32_e32 v50, v42
	v_pk_mul_f32 v[42:43], v[146:147], v[40:41]
	v_mul_f32_e32 v41, 0x3d372713, v40
	v_mul_f32_e32 v41, v41, v40
	v_fmac_f32_e32 v40, v41, v40
	v_mul_f32_e32 v40, 0x3f4c422a, v40
	v_add_f32_e32 v40, v40, v40
	v_mul_f32_e32 v40, 0x3fb8aa3b, v40
	v_exp_f32_e32 v40, v40
	v_add_f32_e32 v41, 1.0, v50
	v_rcp_f32_e32 v50, v41
	v_mov_b32_e32 v41, 1.0
	v_add_f32_e32 v40, 1.0, v40
	v_rcp_f32_e32 v40, v40
	v_mov_b32_dpp v41, v43 row_shr:8 row_mask:0xf bank_mask:0xf
	v_pk_mul_f32 v[34:35], v[82:83], v[86:87]
	v_mov_b32_dpp v45, v57 row_shr:4 row_mask:0xf bank_mask:0xf
	v_fma_f32 v40, v40, -2.0, 1.0
	v_add_f32_e32 v40, 1.0, v40
	v_and_b32_e32 v44, 0xffff0000, v244
	v_fmac_f32_e32 v58, v43, v51
	v_pk_mul_f32 v[52:53], v[42:43], v[40:41]
	v_mov_b32_e32 v51, v38
	v_mov_b32_e32 v147, v57
	ds_bpermute_b32 v40, v184, v53
	v_mul_f32_e32 v41, v34, v53
	v_pk_mul_f32 v[50:51], v[50:51], v[52:53]
	v_pk_mul_f32 v[52:53], v[146:147], v[44:45]
	v_mul_f32_e32 v45, 0x3d372713, v44
	v_mul_f32_e32 v45, v45, v44
	v_fmac_f32_e32 v44, v45, v44
	v_and_b32_e32 v64, 0xffff0000, v246
	v_add_f32_e32 v43, v51, v58
	v_mul_f32_e32 v44, 0x3f4c422a, v44
	ds_bpermute_b32 v42, v184, v58
	v_mul_f32_e32 v58, v50, v43
	v_mul_f32_e32 v43, 0xbfb8aa3b, v64
	v_add_f32_e32 v44, v44, v44
	v_exp_f32_e32 v43, v43
	v_mul_f32_e32 v44, 0x3fb8aa3b, v44
	v_exp_f32_e32 v45, v44
	v_mul_f32_e32 v57, v50, v41
	v_add_f32_e32 v41, 1.0, v43
	v_rcp_f32_e32 v44, v41
	v_add_f32_e32 v41, 1.0, v45
	v_rcp_f32_e32 v41, v41
	v_mov_b32_e32 v51, 1.0
	v_mov_b32_e32 v47, 1.0
	v_lshlrev_b32_e32 v46, 16, v245
	v_fma_f32 v41, v41, -2.0, 1.0
	v_mov_b32_dpp v51, v53 row_shr:8 row_mask:0xf bank_mask:0xf
	v_add_f32_e32 v50, 1.0, v41
	v_mov_b32_dpp v47, v59 row_shr:4 row_mask:0xf bank_mask:0xf
	v_pk_mul_f32 v[50:51], v[52:53], v[50:51]
	v_mov_b32_e32 v45, v39
	v_mov_b32_e32 v147, v59
	v_mov_b32_e32 v61, v145
	ds_bpermute_b32 v41, v184, v51
	v_mul_f32_e32 v52, v35, v51
	v_pk_mul_f32 v[44:45], v[44:45], v[50:51]
	v_pk_mul_f32 v[50:51], v[146:147], v[46:47]
	v_mul_f32_e32 v47, 0x3d372713, v46
	v_mov_b32_dpp v61, v55 row_shr:8 row_mask:0xf bank_mask:0xf
	v_mul_f32_e32 v47, v47, v46
	v_fmac_f32_e32 v55, v53, v61
	v_fmac_f32_e32 v46, v47, v46
	v_lshlrev_b32_e32 v65, 16, v247
	v_add_f32_e32 v45, v45, v55
	v_mul_f32_e32 v46, 0x3f4c422a, v46
	ds_bpermute_b32 v43, v184, v55
	v_mul_f32_e32 v55, v44, v45
	v_mul_f32_e32 v45, 0xbfb8aa3b, v65
	v_add_f32_e32 v46, v46, v46
	v_exp_f32_e32 v45, v45
	v_mul_f32_e32 v46, 0x3fb8aa3b, v46
	v_exp_f32_e32 v46, v46
	v_mul_f32_e32 v59, v44, v52
	v_add_f32_e32 v44, 1.0, v45
	v_rcp_f32_e32 v52, v44
	v_add_f32_e32 v44, 1.0, v46
	v_rcp_f32_e32 v44, v44
	v_mov_b32_e32 v62, v145
	v_mov_b32_e32 v45, 1.0
	s_waitcnt lgkmcnt(4)
	v_pk_fma_f32 v[36:37], v[76:77], v[142:143], v[162:163]
	v_fma_f32 v44, v44, -2.0, 1.0
	v_mov_b32_e32 v49, 1.0
	v_mov_b32_dpp v62, v54 row_shr:8 row_mask:0xf bank_mask:0xf
	v_mov_b32_dpp v45, v51 row_shr:8 row_mask:0xf bank_mask:0xf
	v_add_f32_e32 v44, 1.0, v44
	v_pk_mul_f32 v[32:33], v[78:79], v[142:143]
	v_mov_b32_dpp v49, v60 row_shr:4 row_mask:0xf bank_mask:0xf
	v_and_b32_e32 v48, 0xffff0000, v245
	v_fmac_f32_e32 v54, v51, v62
	v_pk_mul_f32 v[50:51], v[50:51], v[44:45]
	v_mov_b32_e32 v53, v36
	v_mov_b32_e32 v147, v60
	ds_bpermute_b32 v44, v184, v51
	v_mul_f32_e32 v45, v32, v51
	v_pk_mul_f32 v[50:51], v[52:53], v[50:51]
	v_pk_mul_f32 v[52:53], v[146:147], v[48:49]
	v_mul_f32_e32 v49, 0x3d372713, v48
	v_mul_f32_e32 v49, v49, v48
	v_fmac_f32_e32 v48, v49, v48
	v_and_b32_e32 v66, 0xffff0000, v247
	v_add_f32_e32 v47, v51, v54
	v_mul_f32_e32 v48, 0x3f4c422a, v48
	ds_bpermute_b32 v46, v184, v54
	v_mul_f32_e32 v54, v50, v47
	v_mul_f32_e32 v47, 0xbfb8aa3b, v66
	v_add_f32_e32 v48, v48, v48
	v_exp_f32_e32 v47, v47
	v_mul_f32_e32 v48, 0x3fb8aa3b, v48
	v_exp_f32_e32 v49, v48
	v_mul_f32_e32 v60, v50, v45
	v_add_f32_e32 v45, 1.0, v47
	v_rcp_f32_e32 v48, v45
	v_add_f32_e32 v45, 1.0, v49
	v_rcp_f32_e32 v45, v45
	v_mov_b32_e32 v63, v145
	v_mov_b32_e32 v51, 1.0
	v_mov_b32_e32 v49, v37
	v_fma_f32 v45, v45, -2.0, 1.0
	v_mov_b32_dpp v63, v56 row_shr:8 row_mask:0xf bank_mask:0xf
	v_mov_b32_dpp v51, v53 row_shr:8 row_mask:0xf bank_mask:0xf
	v_add_f32_e32 v50, 1.0, v45
	v_fmac_f32_e32 v56, v53, v63
	v_pk_mul_f32 v[50:51], v[52:53], v[50:51]
	ds_bpermute_b32 v45, v184, v51
	ds_bpermute_b32 v47, v184, v56
	v_pk_mul_f32 v[48:49], v[48:49], v[50:51]
	s_mov_b32 s54, 0x25d59000
	v_add_f32_e32 v49, v49, v56
	v_add_co_u32_e32 v50, vcc, s54, v84
	v_mul_f32_e32 v52, v33, v51
	v_mul_f32_e32 v49, v48, v49
	v_addc_co_u32_e32 v51, vcc, 0, v85, vcc
	v_mul_f32_e32 v52, v48, v52
	v_cvt_pk_bf16_f32 v48, v58, v55
	v_cvt_pk_bf16_f32 v49, v54, v49
	global_store_dwordx2 v[50:51], v[48:49], off
	v_add_co_u32_e32 v50, vcc, 0x27d59000, v84
	v_cvt_pk_bf16_f32 v48, v57, v59
	v_cvt_pk_bf16_f32 v49, v60, v52
	s_nop 1
	v_addc_co_u32_e32 v51, vcc, 0, v85, vcc
	global_store_dwordx2 v[50:51], v[48:49], off
	s_and_saveexec_b64 s[54:55], s[6:7]
	s_cbranch_execz .LBB0_194
	s_waitcnt lgkmcnt(0)
	v_pk_fma_f32 v[48:49], v[36:37], v[44:45], v[46:47]
	v_pk_mul_f32 v[36:37], v[32:33], v[44:45]
	v_lshl_add_u64 v[32:33], s[74:75], 0, v[130:131]
	v_pk_fma_f32 v[46:47], v[38:39], v[40:41], v[42:43]
	v_add_co_u32_e32 v38, vcc, 0x2dd41000, v32
	v_pk_mul_f32 v[34:35], v[34:35], v[40:41]
	s_nop 0
	v_addc_co_u32_e32 v39, vcc, 0, v33, vcc
	v_add_co_u32_e32 v32, vcc, 0x2de41000, v32
	global_store_dwordx4 v[38:39], v[34:37], off
	s_nop 0
	v_addc_co_u32_e32 v33, vcc, 0, v33, vcc
	global_store_dwordx4 v[32:33], v[46:49], off
	s_branch .LBB0_194
